# GEMM K-loops: removed the redundant back-to-back s_setprio 0 / s_setprio 1 pair in the middle of each 32-MFMA block (priority stays raised across the block)
# speedup vs baseline: 1.0051x; 1.0051x over previous
; #define PG8_STAGE(bufoff, gbase, voff) do { _Pragma("unroll") for (int _i = 0; _i < 2; ++_i) \
;         __builtin_amdgcn_global_load_lds((const unsigned*)((const char*)(gbase) + (voff)[_i]), (PG8_LAS unsigned*)(lds + (bufoff) + ldsw + _i * 8192), 16, 0, 0); } while (0)
; #define PG8_LDA(dst, b, h) do { _Pragma("unroll") for (int m = 0; m < 4; ++m) _Pragma("unroll") for (int k = 0; k < 2; ++k) dst[m][k] = *(const PG8_LAS bf16x8*)(lds + PG8_SA(b, h) + aoff + m * 2048 + k * 1024); } while (0)
; #define PG8_LDB(dst, b, h) do { _Pragma("unroll") for (int n = 0; n < 2; ++n) _Pragma("unroll") for (int k = 0; k < 2; ++k) dst[n][k] = *(const PG8_LAS bf16x8*)(lds + PG8_SB(b, h) + boff + n * 2048 + k * 1024); } while (0)
; #define PG8_MMA(ai, bj, At, Bt) do { __builtin_amdgcn_s_setprio(1); _Pragma("unroll") for (int m = 0; m < 4; ++m) _Pragma("unroll") for (int n = 0; n < 2; ++n) _Pragma("unroll") for (int k = 0; k < 2; ++k) \
;         acc[ai][bj][m][n] = __builtin_amdgcn_mfma_f32_16x16x32_bf16(Bt[n][k], At[m][k], acc[ai][bj][m][n], 0, 0, 0); __builtin_amdgcn_s_setprio(0); } while (0)
; #define PG8_WAIT_V(n) asm volatile("s_waitcnt vmcnt(" #n ")" ::: "memory")
; #define PG8_WAIT_L(n) asm volatile("s_waitcnt lgkmcnt(" #n ")" ::: "memory")
; template <class Epi, class Sched, bool ALIGN_EPI = false, bool SP2 = false>
; __device__ __forceinline__ void gemm_phase(PG8_LAS unsigned char* lds, const Gemm g, const Sched& S, const Epi& E) {
;     ...
;             const bool last = (t == nt - 2);
;             const char* a1 = cA + (size_t)(t + 1) * kstep;
;             const char* a2 = last ? nA : cA + (size_t)(t + 2) * kstep; const char* b2 = last ? nB : cB + (size_t)(t + 2) * kstep;
;             const char* a3 = a2 + kstep; const char* b3 = b2 + kstep;
;             if (last && has_next) S.a_ready(nxt);
;             if constexpr (SP2) {
;             PG8_LDB(B0, 0, 0); PG8_LDB(B1, 0, 1); PG8_SCHED; PG8_LDA(At, 0, 0); PG8_STAGE(PG8_SA(1, 1), a1 + hstepA, voffA);
;             PG8_WAIT_V(8); PG8_WAIT_L(0); PG8_BAR; PG8_MMA(0, 0, At, B0); PG8_MMA(0, 1, At, B1); PG8_BAR; PG8_SCHED;
;             PG8_LDA(At, 0, 1); PG8_STAGE(PG8_SB(0, 0), b2, voffB); PG8_STAGE(PG8_SB(0, 1), b2 + hstep, voffB); PG8_STAGE(PG8_SA(0, 0), a2, voffA);
;             PG8_WAIT_V(8); PG8_WAIT_L(0); PG8_BAR; PG8_MMA(1, 0, At, B0); PG8_MMA(1, 1, At, B1); PG8_BAR; PG8_SCHED;
.LBB0_103:
	s_add_u32 s44, s42, 0xfffc0080
	s_addc_u32 s45, s43, -1
	s_add_i32 s56, 0, 0x10000
	s_cmp_eq_u32 s55, 12
	s_cselect_b32 s47, s13, s45
	s_cselect_b32 s46, s51, s44
	v_add_u32_e32 v146, s56, v149
	s_cselect_b32 s45, s11, s54
	s_cselect_b32 s44, s52, s53
	s_add_i32 s58, 0, 0x14000
	ds_read_b128 v[158:161], v146
	ds_read_b128 v[162:165], v146 offset:1024
	ds_read_b128 v[166:169], v146 offset:2048
	ds_read_b128 v[170:173], v146 offset:3072
	v_add_u32_e32 v146, s58, v149
	ds_read_b128 v[174:177], v146
	ds_read_b128 v[178:181], v146 offset:1024
	ds_read_b128 v[182:185], v146 offset:2048
	ds_read_b128 v[186:189], v146 offset:3072
	v_lshl_add_u64 v[146:147], s[42:43], 0, v[142:143]
	s_add_i32 m0, s4, 0xc000
	ds_read_b128 v[190:193], v157
	ds_read_b128 v[198:201], v157 offset:1024
	ds_read_b128 v[202:205], v157 offset:2048
	ds_read_b128 v[206:209], v157 offset:3072
	ds_read_b128 v[210:213], v157 offset:4096
	ds_read_b128 v[214:217], v157 offset:5120
	ds_read_b128 v[218:221], v157 offset:6144
	ds_read_b128 v[222:225], v157 offset:7168
	global_load_lds_dwordx4 v[146:147], off
	v_lshl_add_u64 v[146:147], s[42:43], 0, v[144:145]
	s_add_i32 m0, s4, 0xe000
	s_nop 0
	global_load_lds_dwordx4 v[146:147], off
	s_waitcnt vmcnt(8)
	s_waitcnt lgkmcnt(0)
	s_barrier
	s_setprio 1
	s_waitcnt lgkmcnt(0)
	v_mfma_f32_16x16x32_bf16 v[132:135], v[158:161], v[190:193], v[132:135]
	v_mfma_f32_16x16x32_bf16 v[128:131], v[166:169], v[190:193], v[128:131]
	v_mfma_f32_16x16x32_bf16 v[120:123], v[158:161], v[202:205], v[120:123]
	v_mfma_f32_16x16x32_bf16 v[112:115], v[166:169], v[202:205], v[112:115]
	v_mfma_f32_16x16x32_bf16 v[104:107], v[158:161], v[210:213], v[104:107]
	v_mfma_f32_16x16x32_bf16 v[96:99], v[166:169], v[210:213], v[96:99]
	v_mfma_f32_16x16x32_bf16 v[88:91], v[158:161], v[218:221], v[88:91]
	v_mfma_f32_16x16x32_bf16 v[74:77], v[166:169], v[218:221], v[74:77]
	v_mfma_f32_16x16x32_bf16 v[132:135], v[162:165], v[198:201], v[132:135]
	v_mfma_f32_16x16x32_bf16 v[128:131], v[170:173], v[198:201], v[128:131]
	v_mfma_f32_16x16x32_bf16 v[120:123], v[162:165], v[206:209], v[120:123]
	v_mfma_f32_16x16x32_bf16 v[112:115], v[170:173], v[206:209], v[112:115]
	v_mfma_f32_16x16x32_bf16 v[104:107], v[162:165], v[214:217], v[104:107]
	v_mfma_f32_16x16x32_bf16 v[96:99], v[170:173], v[214:217], v[96:99]
	v_mfma_f32_16x16x32_bf16 v[88:91], v[162:165], v[222:225], v[88:91]
	v_mfma_f32_16x16x32_bf16 v[74:77], v[170:173], v[222:225], v[74:77]
	v_mfma_f32_16x16x32_bf16 v[124:127], v[174:177], v[190:193], v[124:127]
	v_mfma_f32_16x16x32_bf16 v[116:119], v[182:185], v[190:193], v[116:119]
	v_mfma_f32_16x16x32_bf16 v[108:111], v[174:177], v[202:205], v[108:111]
	v_mfma_f32_16x16x32_bf16 v[100:103], v[182:185], v[202:205], v[100:103]
	v_mfma_f32_16x16x32_bf16 v[92:95], v[174:177], v[210:213], v[92:95]
	v_mfma_f32_16x16x32_bf16 v[84:87], v[182:185], v[210:213], v[84:87]
	v_mfma_f32_16x16x32_bf16 v[70:73], v[174:177], v[218:221], v[70:73]
	v_mfma_f32_16x16x32_bf16 v[66:69], v[182:185], v[218:221], v[66:69]
	v_mfma_f32_16x16x32_bf16 v[124:127], v[178:181], v[198:201], v[124:127]
	v_mfma_f32_16x16x32_bf16 v[116:119], v[186:189], v[198:201], v[116:119]
	v_mfma_f32_16x16x32_bf16 v[108:111], v[178:181], v[206:209], v[108:111]
	v_mfma_f32_16x16x32_bf16 v[100:103], v[186:189], v[206:209], v[100:103]
	v_mfma_f32_16x16x32_bf16 v[92:95], v[178:181], v[214:217], v[92:95]
	v_mfma_f32_16x16x32_bf16 v[84:87], v[186:189], v[214:217], v[84:87]
	v_mfma_f32_16x16x32_bf16 v[70:73], v[178:181], v[222:225], v[70:73]
	v_mfma_f32_16x16x32_bf16 v[66:69], v[186:189], v[222:225], v[66:69]
	s_setprio 0
	s_barrier
	s_add_i32 s56, s56, s0
	v_lshl_add_u64 v[146:147], s[44:45], 0, v[138:139]
	s_mov_b32 m0, s56
	ds_read_b128 v[190:193], v157 offset:16384
	ds_read_b128 v[198:201], v157 offset:17408
	ds_read_b128 v[202:205], v157 offset:18432
	ds_read_b128 v[206:209], v157 offset:19456
	ds_read_b128 v[210:213], v157 offset:20480
	ds_read_b128 v[214:217], v157 offset:21504
	ds_read_b128 v[218:221], v157 offset:22528
	ds_read_b128 v[222:225], v157 offset:23552
	global_load_lds_dwordx4 v[146:147], off
	s_add_i32 m0, s56, 0x2000
	s_add_u32 s56, s44, 0x40000
	v_lshl_add_u64 v[150:151], s[44:45], 0, v[78:79]
	s_addc_u32 s57, s45, 0
	s_add_i32 s58, s58, s0
	global_load_lds_dwordx4 v[150:151], off
	v_lshl_add_u64 v[154:155], s[56:57], 0, v[138:139]
	s_mov_b32 m0, s58
	v_lshl_add_u64 v[194:195], s[46:47], 0, v[136:137]
	global_load_lds_dwordx4 v[154:155], off
	v_lshl_add_u64 v[154:155], s[56:57], 0, v[78:79]
	s_add_i32 m0, s58, 0x2000
	s_nop 0
	global_load_lds_dwordx4 v[154:155], off
	v_lshl_add_u64 v[154:155], s[46:47], 0, v[140:141]
	s_mov_b32 m0, s4
	s_nop 0
	global_load_lds_dwordx4 v[154:155], off
	s_mov_b32 m0, s5
	s_nop 0
	global_load_lds_dwordx4 v[194:195], off
	s_waitcnt vmcnt(8)
	s_waitcnt lgkmcnt(0)
	s_barrier
; #define PG8_STAGE(bufoff, gbase, voff) do { _Pragma("unroll") for (int _i = 0; _i < 2; ++_i) \
;         __builtin_amdgcn_global_load_lds((const unsigned*)((const char*)(gbase) + (voff)[_i]), (PG8_LAS unsigned*)(lds + (bufoff) + ldsw + _i * 8192), 16, 0, 0); } while (0)
; #define PG8_LDA(dst, b, h) do { _Pragma("unroll") for (int m = 0; m < 4; ++m) _Pragma("unroll") for (int k = 0; k < 2; ++k) dst[m][k] = *(const PG8_LAS bf16x8*)(lds + PG8_SA(b, h) + aoff + m * 2048 + k * 1024); } while (0)
; #define PG8_LDB(dst, b, h) do { _Pragma("unroll") for (int n = 0; n < 2; ++n) _Pragma("unroll") for (int k = 0; k < 2; ++k) dst[n][k] = *(const PG8_LAS bf16x8*)(lds + PG8_SB(b, h) + boff + n * 2048 + k * 1024); } while (0)
; #define PG8_MMA(ai, bj, At, Bt) do { __builtin_amdgcn_s_setprio(1); _Pragma("unroll") for (int m = 0; m < 4; ++m) _Pragma("unroll") for (int n = 0; n < 2; ++n) _Pragma("unroll") for (int k = 0; k < 2; ++k) \
;         acc[ai][bj][m][n] = __builtin_amdgcn_mfma_f32_16x16x32_bf16(Bt[n][k], At[m][k], acc[ai][bj][m][n], 0, 0, 0); __builtin_amdgcn_s_setprio(0); } while (0)
; #define PG8_WAIT_V(n) asm volatile("s_waitcnt vmcnt(" #n ")" ::: "memory")
; #define PG8_WAIT_L(n) asm volatile("s_waitcnt lgkmcnt(" #n ")" ::: "memory")
; #define PG8_BAR __builtin_amdgcn_s_barrier()
; #define PG8_SCHED __builtin_amdgcn_sched_barrier(0)
; template <class Epi, class Sched, bool ALIGN_EPI = false, bool SP2 = false>
; __device__ __forceinline__ void gemm_phase(PG8_LAS unsigned char* lds, const Gemm g, const Sched& S, const Epi& E) {
;     ...
;             PG8_WAIT_V(8); PG8_WAIT_L(0); PG8_BAR; PG8_MMA(1, 0, At, B0); PG8_MMA(1, 1, At, B1); PG8_BAR; PG8_SCHED;
;             PG8_LDB(B0, 1, 0); PG8_LDB(B1, 1, 1); PG8_SCHED; PG8_LDA(At, 1, 0); PG8_STAGE(PG8_SA(0, 1), a2 + hstepA, voffA);
;             PG8_WAIT_V(8); PG8_WAIT_L(0); PG8_BAR; PG8_MMA(0, 0, At, B0); PG8_MMA(0, 1, At, B1); PG8_BAR; PG8_SCHED;
	s_setprio 1
	s_waitcnt lgkmcnt(0)
	v_mfma_f32_16x16x32_bf16 v[62:65], v[158:161], v[190:193], v[62:65]
	v_mfma_f32_16x16x32_bf16 v[58:61], v[166:169], v[190:193], v[58:61]
	v_mfma_f32_16x16x32_bf16 v[50:53], v[158:161], v[202:205], v[50:53]
	v_mfma_f32_16x16x32_bf16 v[42:45], v[166:169], v[202:205], v[42:45]
	v_mfma_f32_16x16x32_bf16 v[34:37], v[158:161], v[210:213], v[34:37]
	v_mfma_f32_16x16x32_bf16 v[26:29], v[166:169], v[210:213], v[26:29]
	v_mfma_f32_16x16x32_bf16 v[18:21], v[158:161], v[218:221], v[18:21]
	v_mfma_f32_16x16x32_bf16 v[10:13], v[166:169], v[218:221], v[10:13]
	v_mfma_f32_16x16x32_bf16 v[62:65], v[162:165], v[198:201], v[62:65]
	v_mfma_f32_16x16x32_bf16 v[58:61], v[170:173], v[198:201], v[58:61]
	v_mfma_f32_16x16x32_bf16 v[50:53], v[162:165], v[206:209], v[50:53]
	v_mfma_f32_16x16x32_bf16 v[42:45], v[170:173], v[206:209], v[42:45]
	v_mfma_f32_16x16x32_bf16 v[34:37], v[162:165], v[214:217], v[34:37]
	v_mfma_f32_16x16x32_bf16 v[26:29], v[170:173], v[214:217], v[26:29]
	v_mfma_f32_16x16x32_bf16 v[18:21], v[162:165], v[222:225], v[18:21]
	v_mfma_f32_16x16x32_bf16 v[10:13], v[170:173], v[222:225], v[10:13]
	v_mfma_f32_16x16x32_bf16 v[54:57], v[174:177], v[190:193], v[54:57]
	v_mfma_f32_16x16x32_bf16 v[46:49], v[182:185], v[190:193], v[46:49]
	v_mfma_f32_16x16x32_bf16 v[38:41], v[174:177], v[202:205], v[38:41]
	v_mfma_f32_16x16x32_bf16 v[30:33], v[182:185], v[202:205], v[30:33]
	v_mfma_f32_16x16x32_bf16 v[22:25], v[174:177], v[210:213], v[22:25]
	v_mfma_f32_16x16x32_bf16 v[14:17], v[182:185], v[210:213], v[14:17]
	v_mfma_f32_16x16x32_bf16 v[6:9], v[174:177], v[218:221], v[6:9]
	v_mfma_f32_16x16x32_bf16 v[2:5], v[182:185], v[218:221], v[2:5]
	v_mfma_f32_16x16x32_bf16 v[54:57], v[178:181], v[198:201], v[54:57]
	v_mfma_f32_16x16x32_bf16 v[46:49], v[186:189], v[198:201], v[46:49]
	v_mfma_f32_16x16x32_bf16 v[38:41], v[178:181], v[206:209], v[38:41]
	v_mfma_f32_16x16x32_bf16 v[30:33], v[186:189], v[206:209], v[30:33]
	v_mfma_f32_16x16x32_bf16 v[22:25], v[178:181], v[214:217], v[22:25]
	v_mfma_f32_16x16x32_bf16 v[14:17], v[186:189], v[214:217], v[14:17]
	v_mfma_f32_16x16x32_bf16 v[6:9], v[178:181], v[222:225], v[6:9]
	v_mfma_f32_16x16x32_bf16 v[2:5], v[186:189], v[222:225], v[2:5]
	s_setprio 0
	s_barrier
	s_add_i32 s56, 0, 0x18000
	v_add_u32_e32 v148, s56, v149
	s_add_i32 s57, 0, 0x1c000
	ds_read_b128 v[158:161], v148
	ds_read_b128 v[162:165], v148 offset:1024
	ds_read_b128 v[166:169], v148 offset:2048
	ds_read_b128 v[170:173], v148 offset:3072
	v_add_u32_e32 v148, s57, v149
	ds_read_b128 v[174:177], v148
	ds_read_b128 v[178:181], v148 offset:1024
	ds_read_b128 v[182:185], v148 offset:2048
	ds_read_b128 v[186:189], v148 offset:3072
	s_add_u32 s46, s46, 0x40000
	s_addc_u32 s47, s47, 0
	s_mov_b32 m0, s16
	v_lshl_add_u64 v[226:227], s[46:47], 0, v[140:141]
	ds_read_b128 v[190:193], v157 offset:32768
	ds_read_b128 v[198:201], v157 offset:33792
	ds_read_b128 v[202:205], v157 offset:34816
	ds_read_b128 v[206:209], v157 offset:35840
	ds_read_b128 v[210:213], v157 offset:36864
	ds_read_b128 v[214:217], v157 offset:37888
	ds_read_b128 v[218:221], v157 offset:38912
	ds_read_b128 v[222:225], v157 offset:39936
	global_load_lds_dwordx4 v[226:227], off
	v_lshl_add_u64 v[226:227], s[46:47], 0, v[136:137]
	s_mov_b32 m0, s17
	s_nop 0
	global_load_lds_dwordx4 v[226:227], off
	s_waitcnt vmcnt(8)
	s_waitcnt lgkmcnt(0)
	s_barrier
	s_setprio 1
	s_waitcnt lgkmcnt(0)
	v_mfma_f32_16x16x32_bf16 v[132:135], v[158:161], v[190:193], v[132:135]
	v_mfma_f32_16x16x32_bf16 v[128:131], v[166:169], v[190:193], v[128:131]
	v_mfma_f32_16x16x32_bf16 v[120:123], v[158:161], v[202:205], v[120:123]
	v_mfma_f32_16x16x32_bf16 v[112:115], v[166:169], v[202:205], v[112:115]
	v_mfma_f32_16x16x32_bf16 v[104:107], v[158:161], v[210:213], v[104:107]
	v_mfma_f32_16x16x32_bf16 v[96:99], v[166:169], v[210:213], v[96:99]
	v_mfma_f32_16x16x32_bf16 v[88:91], v[158:161], v[218:221], v[88:91]
	v_mfma_f32_16x16x32_bf16 v[74:77], v[166:169], v[218:221], v[74:77]
	v_mfma_f32_16x16x32_bf16 v[132:135], v[162:165], v[198:201], v[132:135]
	v_mfma_f32_16x16x32_bf16 v[128:131], v[170:173], v[198:201], v[128:131]
	v_mfma_f32_16x16x32_bf16 v[120:123], v[162:165], v[206:209], v[120:123]
	v_mfma_f32_16x16x32_bf16 v[112:115], v[170:173], v[206:209], v[112:115]
	v_mfma_f32_16x16x32_bf16 v[104:107], v[162:165], v[214:217], v[104:107]
	v_mfma_f32_16x16x32_bf16 v[96:99], v[170:173], v[214:217], v[96:99]
	v_mfma_f32_16x16x32_bf16 v[88:91], v[162:165], v[222:225], v[88:91]
	v_mfma_f32_16x16x32_bf16 v[74:77], v[170:173], v[222:225], v[74:77]
	v_mfma_f32_16x16x32_bf16 v[124:127], v[174:177], v[190:193], v[124:127]
	v_mfma_f32_16x16x32_bf16 v[116:119], v[182:185], v[190:193], v[116:119]
	v_mfma_f32_16x16x32_bf16 v[108:111], v[174:177], v[202:205], v[108:111]
	v_mfma_f32_16x16x32_bf16 v[100:103], v[182:185], v[202:205], v[100:103]
	v_mfma_f32_16x16x32_bf16 v[92:95], v[174:177], v[210:213], v[92:95]
	v_mfma_f32_16x16x32_bf16 v[84:87], v[182:185], v[210:213], v[84:87]
	v_mfma_f32_16x16x32_bf16 v[70:73], v[174:177], v[218:221], v[70:73]
	v_mfma_f32_16x16x32_bf16 v[66:69], v[182:185], v[218:221], v[66:69]
	v_mfma_f32_16x16x32_bf16 v[124:127], v[178:181], v[198:201], v[124:127]
	v_mfma_f32_16x16x32_bf16 v[116:119], v[186:189], v[198:201], v[116:119]
	v_mfma_f32_16x16x32_bf16 v[108:111], v[178:181], v[206:209], v[108:111]
	v_mfma_f32_16x16x32_bf16 v[100:103], v[186:189], v[206:209], v[100:103]
	v_mfma_f32_16x16x32_bf16 v[92:95], v[178:181], v[214:217], v[92:95]
	v_mfma_f32_16x16x32_bf16 v[84:87], v[186:189], v[214:217], v[84:87]
	v_mfma_f32_16x16x32_bf16 v[70:73], v[178:181], v[222:225], v[70:73]
	v_mfma_f32_16x16x32_bf16 v[66:69], v[186:189], v[222:225], v[66:69]
	s_setprio 0
	s_barrier
; #define PG8_STAGE(bufoff, gbase, voff) do { _Pragma("unroll") for (int _i = 0; _i < 2; ++_i) \
;         __builtin_amdgcn_global_load_lds((const unsigned*)((const char*)(gbase) + (voff)[_i]), (PG8_LAS unsigned*)(lds + (bufoff) + ldsw + _i * 8192), 16, 0, 0); } while (0)
; #define PG8_LDA(dst, b, h) do { _Pragma("unroll") for (int m = 0; m < 4; ++m) _Pragma("unroll") for (int k = 0; k < 2; ++k) dst[m][k] = *(const PG8_LAS bf16x8*)(lds + PG8_SA(b, h) + aoff + m * 2048 + k * 1024); } while (0)
; #define PG8_LDB(dst, b, h) do { _Pragma("unroll") for (int n = 0; n < 2; ++n) _Pragma("unroll") for (int k = 0; k < 2; ++k) dst[n][k] = *(const PG8_LAS bf16x8*)(lds + PG8_SB(b, h) + boff + n * 2048 + k * 1024); } while (0)
; template <class Epi, class Sched, bool ALIGN_EPI = false, bool SP2 = false>
; __device__ __forceinline__ void gemm_phase(PG8_LAS unsigned char* lds, const Gemm g, const Sched& S, const Epi& E) {
;     ...
;         for (int t = 0; t < nt; t += 2) {
;             const bool last = (t == nt - 2);
;             const char* a1 = cA + (size_t)(t + 1) * kstep;
;             const char* a2 = last ? nA : cA + (size_t)(t + 2) * kstep; const char* b2 = last ? nB : cB + (size_t)(t + 2) * kstep;
;             const char* a3 = a2 + kstep; const char* b3 = b2 + kstep;
;             if (last && has_next) S.a_ready(nxt);
;             if constexpr (SP2) {
;             PG8_LDB(B0, 0, 0); PG8_LDB(B1, 0, 1); PG8_SCHED; PG8_LDA(At, 0, 0); PG8_STAGE(PG8_SA(1, 1), a1 + hstepA, voffA);
;             PG8_WAIT_V(8); PG8_WAIT_L(0); PG8_BAR; PG8_MMA(0, 0, At, B0); PG8_MMA(0, 1, At, B1); PG8_BAR; PG8_SCHED;
;             PG8_LDA(At, 0, 1); PG8_STAGE(PG8_SB(0, 0), b2, voffB); PG8_STAGE(PG8_SB(0, 1), b2 + hstep, voffB); PG8_STAGE(PG8_SA(0, 0), a2, voffA);
;             PG8_WAIT_V(8); PG8_WAIT_L(0); PG8_BAR; PG8_MMA(1, 0, At, B0); PG8_MMA(1, 1, At, B1); PG8_BAR; PG8_SCHED;
;             PG8_LDB(B0, 1, 0); PG8_LDB(B1, 1, 1); PG8_SCHED; PG8_LDA(At, 1, 0); PG8_STAGE(PG8_SA(0, 1), a2 + hstepA, voffA);
;             PG8_WAIT_V(8); PG8_WAIT_L(0); PG8_BAR; PG8_MMA(0, 0, At, B0); PG8_MMA(0, 1, At, B1); PG8_BAR; PG8_SCHED;
;             PG8_LDA(At, 1, 1); PG8_STAGE(PG8_SB(1, 0), b3, voffB); PG8_STAGE(PG8_SB(1, 1), b3 + hstep, voffB); PG8_STAGE(PG8_SA(1, 0), a3, voffA);
;             PG8_WAIT_V(8); PG8_WAIT_L(0); PG8_BAR; PG8_MMA(1, 0, At, B0); PG8_MMA(1, 1, At, B1); PG8_BAR; PG8_SCHED;
	s_add_i32 s46, s56, s0
	v_lshl_add_u64 v[146:147], v[146:147], 0, s[26:27]
	s_mov_b32 m0, s46
	ds_read_b128 v[190:193], v157 offset:49152
	ds_read_b128 v[198:201], v157 offset:50176
	ds_read_b128 v[202:205], v157 offset:51200
	ds_read_b128 v[206:209], v157 offset:52224
	ds_read_b128 v[210:213], v157 offset:53248
	ds_read_b128 v[214:217], v157 offset:54272
	ds_read_b128 v[218:221], v157 offset:55296
	ds_read_b128 v[222:225], v157 offset:56320
	global_load_lds_dwordx4 v[146:147], off
	s_add_i32 m0, s46, 0x2000
	s_add_u32 s44, s44, 0x40080
	v_lshl_add_u64 v[146:147], v[150:151], 0, s[26:27]
	s_addc_u32 s45, s45, 0
	s_add_i32 s46, s57, s0
	global_load_lds_dwordx4 v[146:147], off
	v_lshl_add_u64 v[146:147], s[44:45], 0, v[138:139]
	s_mov_b32 m0, s46
	s_nop 0
	global_load_lds_dwordx4 v[146:147], off
	v_lshl_add_u64 v[146:147], s[44:45], 0, v[78:79]
	s_add_i32 m0, s46, 0x2000
	s_nop 0
	global_load_lds_dwordx4 v[146:147], off
	v_lshl_add_u64 v[146:147], v[154:155], 0, s[26:27]
	s_mov_b32 m0, s24
	s_nop 0
	global_load_lds_dwordx4 v[146:147], off
	v_lshl_add_u64 v[146:147], v[194:195], 0, s[26:27]
	s_mov_b32 m0, s25
	s_nop 0
	global_load_lds_dwordx4 v[146:147], off
	s_waitcnt vmcnt(8)
	s_waitcnt lgkmcnt(0)
	s_barrier
	s_setprio 1
	s_waitcnt lgkmcnt(0)
	v_mfma_f32_16x16x32_bf16 v[62:65], v[158:161], v[190:193], v[62:65]
	v_mfma_f32_16x16x32_bf16 v[58:61], v[166:169], v[190:193], v[58:61]
	v_mfma_f32_16x16x32_bf16 v[50:53], v[158:161], v[202:205], v[50:53]
	v_mfma_f32_16x16x32_bf16 v[42:45], v[166:169], v[202:205], v[42:45]
	v_mfma_f32_16x16x32_bf16 v[34:37], v[158:161], v[210:213], v[34:37]
	v_mfma_f32_16x16x32_bf16 v[26:29], v[166:169], v[210:213], v[26:29]
	v_mfma_f32_16x16x32_bf16 v[18:21], v[158:161], v[218:221], v[18:21]
	v_mfma_f32_16x16x32_bf16 v[10:13], v[166:169], v[218:221], v[10:13]
	v_mfma_f32_16x16x32_bf16 v[62:65], v[162:165], v[198:201], v[62:65]
	v_mfma_f32_16x16x32_bf16 v[58:61], v[170:173], v[198:201], v[58:61]
	v_mfma_f32_16x16x32_bf16 v[50:53], v[162:165], v[206:209], v[50:53]
	v_mfma_f32_16x16x32_bf16 v[42:45], v[170:173], v[206:209], v[42:45]
	v_mfma_f32_16x16x32_bf16 v[34:37], v[162:165], v[214:217], v[34:37]
	v_mfma_f32_16x16x32_bf16 v[26:29], v[170:173], v[214:217], v[26:29]
	v_mfma_f32_16x16x32_bf16 v[18:21], v[162:165], v[222:225], v[18:21]
	v_mfma_f32_16x16x32_bf16 v[10:13], v[170:173], v[222:225], v[10:13]
	v_mfma_f32_16x16x32_bf16 v[54:57], v[174:177], v[190:193], v[54:57]
	v_mfma_f32_16x16x32_bf16 v[46:49], v[182:185], v[190:193], v[46:49]
	v_mfma_f32_16x16x32_bf16 v[38:41], v[174:177], v[202:205], v[38:41]
	v_mfma_f32_16x16x32_bf16 v[30:33], v[182:185], v[202:205], v[30:33]
	v_mfma_f32_16x16x32_bf16 v[22:25], v[174:177], v[210:213], v[22:25]
	v_mfma_f32_16x16x32_bf16 v[14:17], v[182:185], v[210:213], v[14:17]
	v_mfma_f32_16x16x32_bf16 v[6:9], v[174:177], v[218:221], v[6:9]
	v_mfma_f32_16x16x32_bf16 v[2:5], v[182:185], v[218:221], v[2:5]
	v_mfma_f32_16x16x32_bf16 v[54:57], v[178:181], v[198:201], v[54:57]
	v_mfma_f32_16x16x32_bf16 v[46:49], v[186:189], v[198:201], v[46:49]
	v_mfma_f32_16x16x32_bf16 v[38:41], v[178:181], v[206:209], v[38:41]
	v_mfma_f32_16x16x32_bf16 v[30:33], v[186:189], v[206:209], v[30:33]
	v_mfma_f32_16x16x32_bf16 v[22:25], v[178:181], v[214:217], v[22:25]
	v_mfma_f32_16x16x32_bf16 v[14:17], v[186:189], v[214:217], v[14:17]
	v_mfma_f32_16x16x32_bf16 v[6:9], v[178:181], v[222:225], v[6:9]
	v_mfma_f32_16x16x32_bf16 v[2:5], v[186:189], v[222:225], v[2:5]
	s_setprio 0
	s_barrier
	s_add_i32 s55, s55, 2
	s_add_u32 s42, s42, 0x100
	s_addc_u32 s43, s43, 0
	s_add_u32 s53, s53, 0x100
	s_addc_u32 s54, s54, 0
	s_cmp_gt_u32 s55, 13
	s_cbranch_scc0 .LBB0_103
	s_and_b64 vcc, exec, s[8:9]
	s_cbranch_vccz .LBB0_106
	s_barrier

; #define PG8_STAGE(bufoff, gbase, voff) do { _Pragma("unroll") for (int _i = 0; _i < 2; ++_i) \
;         __builtin_amdgcn_global_load_lds((const unsigned*)((const char*)(gbase) + (voff)[_i]), (PG8_LAS unsigned*)(lds + (bufoff) + ldsw + _i * 8192), 16, 0, 0); } while (0)
; #define PG8_LDA(dst, b, h) do { _Pragma("unroll") for (int m = 0; m < 4; ++m) _Pragma("unroll") for (int k = 0; k < 2; ++k) dst[m][k] = *(const PG8_LAS bf16x8*)(lds + PG8_SA(b, h) + aoff + m * 2048 + k * 1024); } while (0)
; #define PG8_LDB(dst, b, h) do { _Pragma("unroll") for (int n = 0; n < 2; ++n) _Pragma("unroll") for (int k = 0; k < 2; ++k) dst[n][k] = *(const PG8_LAS bf16x8*)(lds + PG8_SB(b, h) + boff + n * 2048 + k * 1024); } while (0)
; #define PG8_MMA(ai, bj, At, Bt) do { __builtin_amdgcn_s_setprio(1); _Pragma("unroll") for (int m = 0; m < 4; ++m) _Pragma("unroll") for (int n = 0; n < 2; ++n) _Pragma("unroll") for (int k = 0; k < 2; ++k) \
;         acc[ai][bj][m][n] = __builtin_amdgcn_mfma_f32_16x16x32_bf16(Bt[n][k], At[m][k], acc[ai][bj][m][n], 0, 0, 0); __builtin_amdgcn_s_setprio(0); } while (0)
; #define PG8_WAIT_V(n) asm volatile("s_waitcnt vmcnt(" #n ")" ::: "memory")
; #define PG8_WAIT_L(n) asm volatile("s_waitcnt lgkmcnt(" #n ")" ::: "memory")
; template <class Epi, class Sched, bool ALIGN_EPI = false, bool SP2 = false>
; __device__ __forceinline__ void gemm_phase(PG8_LAS unsigned char* lds, const Gemm g, const Sched& S, const Epi& E) {
;     ...
;             const bool last = (t == nt - 2);
;             const char* a1 = cA + (size_t)(t + 1) * kstep;
;             const char* a2 = last ? nA : cA + (size_t)(t + 2) * kstep; const char* b2 = last ? nB : cB + (size_t)(t + 2) * kstep;
;             const char* a3 = a2 + kstep; const char* b3 = b2 + kstep;
;             if (last && has_next) S.a_ready(nxt);
;             if constexpr (SP2) {
;             PG8_LDB(B0, 0, 0); PG8_LDB(B1, 0, 1); PG8_SCHED; PG8_LDA(At, 0, 0); PG8_STAGE(PG8_SA(1, 1), a1 + hstepA, voffA);
;             PG8_WAIT_V(8); PG8_WAIT_L(0); PG8_BAR; PG8_MMA(0, 0, At, B0); PG8_MMA(0, 1, At, B1); PG8_BAR; PG8_SCHED;
;             PG8_LDA(At, 0, 1); PG8_STAGE(PG8_SB(0, 0), b2, voffB); PG8_STAGE(PG8_SB(0, 1), b2 + hstep, voffB); PG8_STAGE(PG8_SA(0, 0), a2, voffA);
;             PG8_WAIT_V(8); PG8_WAIT_L(0); PG8_BAR; PG8_MMA(1, 0, At, B0); PG8_MMA(1, 1, At, B1); PG8_BAR; PG8_SCHED;
.LBB0_370:
	s_add_u32 s46, s44, 0xfffc0080
	s_addc_u32 s47, s45, -1
	s_add_i32 s57, 0, 0x10000
	s_cmp_eq_u32 s56, 12
	s_cselect_b32 s49, s19, s47
	s_cselect_b32 s48, s52, s46
	v_add_u32_e32 v148, s57, v151
	s_cselect_b32 s47, s13, s55
	s_cselect_b32 s46, s53, s54
	s_waitcnt lgkmcnt(0)
	s_add_i32 s60, 0, 0x14000
	ds_read_b128 v[160:163], v148
	ds_read_b128 v[164:167], v148 offset:1024
	ds_read_b128 v[168:171], v148 offset:2048
	ds_read_b128 v[172:175], v148 offset:3072
	v_add_u32_e32 v148, s60, v151
	ds_read_b128 v[176:179], v148
	ds_read_b128 v[180:183], v148 offset:1024
	ds_read_b128 v[184:187], v148 offset:2048
	ds_read_b128 v[188:191], v148 offset:3072
	v_lshl_add_u64 v[148:149], s[44:45], 0, v[144:145]
	s_add_i32 m0, s4, 0xc000
	ds_read_b128 v[192:195], v159
	ds_read_b128 v[198:201], v159 offset:1024
	ds_read_b128 v[202:205], v159 offset:2048
	ds_read_b128 v[206:209], v159 offset:3072
	ds_read_b128 v[210:213], v159 offset:4096
	ds_read_b128 v[214:217], v159 offset:5120
	ds_read_b128 v[218:221], v159 offset:6144
	ds_read_b128 v[222:225], v159 offset:7168
	global_load_lds_dwordx4 v[148:149], off
	v_lshl_add_u64 v[148:149], s[44:45], 0, v[146:147]
	s_add_i32 m0, s4, 0xe000
	s_nop 0
	global_load_lds_dwordx4 v[148:149], off
	s_waitcnt vmcnt(8)
	s_waitcnt lgkmcnt(0)
	s_barrier
	s_setprio 1
	s_waitcnt lgkmcnt(0)
	v_mfma_f32_16x16x32_bf16 v[132:135], v[160:163], v[192:195], v[132:135]
	v_mfma_f32_16x16x32_bf16 v[128:131], v[168:171], v[192:195], v[128:131]
	v_mfma_f32_16x16x32_bf16 v[120:123], v[160:163], v[202:205], v[120:123]
	v_mfma_f32_16x16x32_bf16 v[112:115], v[168:171], v[202:205], v[112:115]
	v_mfma_f32_16x16x32_bf16 v[104:107], v[160:163], v[210:213], v[104:107]
	v_mfma_f32_16x16x32_bf16 v[96:99], v[168:171], v[210:213], v[96:99]
	v_mfma_f32_16x16x32_bf16 v[88:91], v[160:163], v[218:221], v[88:91]
	v_mfma_f32_16x16x32_bf16 v[74:77], v[168:171], v[218:221], v[74:77]
	v_mfma_f32_16x16x32_bf16 v[132:135], v[164:167], v[198:201], v[132:135]
	v_mfma_f32_16x16x32_bf16 v[128:131], v[172:175], v[198:201], v[128:131]
	v_mfma_f32_16x16x32_bf16 v[120:123], v[164:167], v[206:209], v[120:123]
	v_mfma_f32_16x16x32_bf16 v[112:115], v[172:175], v[206:209], v[112:115]
	v_mfma_f32_16x16x32_bf16 v[104:107], v[164:167], v[214:217], v[104:107]
	v_mfma_f32_16x16x32_bf16 v[96:99], v[172:175], v[214:217], v[96:99]
	v_mfma_f32_16x16x32_bf16 v[88:91], v[164:167], v[222:225], v[88:91]
	v_mfma_f32_16x16x32_bf16 v[74:77], v[172:175], v[222:225], v[74:77]
	v_mfma_f32_16x16x32_bf16 v[124:127], v[176:179], v[192:195], v[124:127]
	v_mfma_f32_16x16x32_bf16 v[116:119], v[184:187], v[192:195], v[116:119]
	v_mfma_f32_16x16x32_bf16 v[108:111], v[176:179], v[202:205], v[108:111]
	v_mfma_f32_16x16x32_bf16 v[100:103], v[184:187], v[202:205], v[100:103]
	v_mfma_f32_16x16x32_bf16 v[92:95], v[176:179], v[210:213], v[92:95]
	v_mfma_f32_16x16x32_bf16 v[84:87], v[184:187], v[210:213], v[84:87]
	v_mfma_f32_16x16x32_bf16 v[70:73], v[176:179], v[218:221], v[70:73]
	v_mfma_f32_16x16x32_bf16 v[66:69], v[184:187], v[218:221], v[66:69]
	v_mfma_f32_16x16x32_bf16 v[124:127], v[180:183], v[198:201], v[124:127]
	v_mfma_f32_16x16x32_bf16 v[116:119], v[188:191], v[198:201], v[116:119]
	v_mfma_f32_16x16x32_bf16 v[108:111], v[180:183], v[206:209], v[108:111]
	v_mfma_f32_16x16x32_bf16 v[100:103], v[188:191], v[206:209], v[100:103]
	v_mfma_f32_16x16x32_bf16 v[92:95], v[180:183], v[214:217], v[92:95]
	v_mfma_f32_16x16x32_bf16 v[84:87], v[188:191], v[214:217], v[84:87]
	v_mfma_f32_16x16x32_bf16 v[70:73], v[180:183], v[222:225], v[70:73]
	v_mfma_f32_16x16x32_bf16 v[66:69], v[188:191], v[222:225], v[66:69]
	s_setprio 0
	s_barrier
	s_add_i32 s57, s57, s0
	v_lshl_add_u64 v[148:149], s[46:47], 0, v[138:139]
	s_mov_b32 m0, s57
	ds_read_b128 v[192:195], v159 offset:16384
	ds_read_b128 v[198:201], v159 offset:17408
	ds_read_b128 v[202:205], v159 offset:18432
	ds_read_b128 v[206:209], v159 offset:19456
	ds_read_b128 v[210:213], v159 offset:20480
	ds_read_b128 v[214:217], v159 offset:21504
	ds_read_b128 v[218:221], v159 offset:22528
	ds_read_b128 v[222:225], v159 offset:23552
	global_load_lds_dwordx4 v[148:149], off
	s_add_i32 m0, s57, 0x2000
	s_add_u32 s58, s46, 0x40000
	v_lshl_add_u64 v[152:153], s[46:47], 0, v[78:79]
	s_addc_u32 s59, s47, 0
	s_add_i32 s57, s60, s0
	global_load_lds_dwordx4 v[152:153], off
	v_lshl_add_u64 v[156:157], s[58:59], 0, v[138:139]
	s_mov_b32 m0, s57
	v_lshl_add_u64 v[226:227], s[48:49], 0, v[136:137]
	global_load_lds_dwordx4 v[156:157], off
	v_lshl_add_u64 v[156:157], s[58:59], 0, v[78:79]
	s_add_i32 m0, s57, 0x2000
	s_nop 0
	global_load_lds_dwordx4 v[156:157], off
	v_lshl_add_u64 v[156:157], s[48:49], 0, v[140:141]
	s_mov_b32 m0, s4
	s_nop 0
	global_load_lds_dwordx4 v[156:157], off
	s_mov_b32 m0, s5
	s_nop 0
	global_load_lds_dwordx4 v[226:227], off
	s_waitcnt vmcnt(8)
	s_waitcnt lgkmcnt(0)
	s_barrier
; #define PG8_STAGE(bufoff, gbase, voff) do { _Pragma("unroll") for (int _i = 0; _i < 2; ++_i) \
;         __builtin_amdgcn_global_load_lds((const unsigned*)((const char*)(gbase) + (voff)[_i]), (PG8_LAS unsigned*)(lds + (bufoff) + ldsw + _i * 8192), 16, 0, 0); } while (0)
; #define PG8_LDA(dst, b, h) do { _Pragma("unroll") for (int m = 0; m < 4; ++m) _Pragma("unroll") for (int k = 0; k < 2; ++k) dst[m][k] = *(const PG8_LAS bf16x8*)(lds + PG8_SA(b, h) + aoff + m * 2048 + k * 1024); } while (0)
; #define PG8_LDB(dst, b, h) do { _Pragma("unroll") for (int n = 0; n < 2; ++n) _Pragma("unroll") for (int k = 0; k < 2; ++k) dst[n][k] = *(const PG8_LAS bf16x8*)(lds + PG8_SB(b, h) + boff + n * 2048 + k * 1024); } while (0)
; #define PG8_MMA(ai, bj, At, Bt) do { __builtin_amdgcn_s_setprio(1); _Pragma("unroll") for (int m = 0; m < 4; ++m) _Pragma("unroll") for (int n = 0; n < 2; ++n) _Pragma("unroll") for (int k = 0; k < 2; ++k) \
;         acc[ai][bj][m][n] = __builtin_amdgcn_mfma_f32_16x16x32_bf16(Bt[n][k], At[m][k], acc[ai][bj][m][n], 0, 0, 0); __builtin_amdgcn_s_setprio(0); } while (0)
; #define PG8_WAIT_V(n) asm volatile("s_waitcnt vmcnt(" #n ")" ::: "memory")
; #define PG8_WAIT_L(n) asm volatile("s_waitcnt lgkmcnt(" #n ")" ::: "memory")
; #define PG8_BAR __builtin_amdgcn_s_barrier()
; #define PG8_SCHED __builtin_amdgcn_sched_barrier(0)
; template <class Epi, class Sched, bool ALIGN_EPI = false, bool SP2 = false>
; __device__ __forceinline__ void gemm_phase(PG8_LAS unsigned char* lds, const Gemm g, const Sched& S, const Epi& E) {
;     ...
;             PG8_WAIT_V(8); PG8_WAIT_L(0); PG8_BAR; PG8_MMA(1, 0, At, B0); PG8_MMA(1, 1, At, B1); PG8_BAR; PG8_SCHED;
;             PG8_LDB(B0, 1, 0); PG8_LDB(B1, 1, 1); PG8_SCHED; PG8_LDA(At, 1, 0); PG8_STAGE(PG8_SA(0, 1), a2 + hstepA, voffA);
;             PG8_WAIT_V(8); PG8_WAIT_L(0); PG8_BAR; PG8_MMA(0, 0, At, B0); PG8_MMA(0, 1, At, B1); PG8_BAR; PG8_SCHED;
	s_setprio 1
	s_waitcnt lgkmcnt(0)
	v_mfma_f32_16x16x32_bf16 v[62:65], v[160:163], v[192:195], v[62:65]
	v_mfma_f32_16x16x32_bf16 v[58:61], v[168:171], v[192:195], v[58:61]
	v_mfma_f32_16x16x32_bf16 v[50:53], v[160:163], v[202:205], v[50:53]
	v_mfma_f32_16x16x32_bf16 v[42:45], v[168:171], v[202:205], v[42:45]
	v_mfma_f32_16x16x32_bf16 v[34:37], v[160:163], v[210:213], v[34:37]
	v_mfma_f32_16x16x32_bf16 v[26:29], v[168:171], v[210:213], v[26:29]
	v_mfma_f32_16x16x32_bf16 v[18:21], v[160:163], v[218:221], v[18:21]
	v_mfma_f32_16x16x32_bf16 v[10:13], v[168:171], v[218:221], v[10:13]
	v_mfma_f32_16x16x32_bf16 v[62:65], v[164:167], v[198:201], v[62:65]
	v_mfma_f32_16x16x32_bf16 v[58:61], v[172:175], v[198:201], v[58:61]
	v_mfma_f32_16x16x32_bf16 v[50:53], v[164:167], v[206:209], v[50:53]
	v_mfma_f32_16x16x32_bf16 v[42:45], v[172:175], v[206:209], v[42:45]
	v_mfma_f32_16x16x32_bf16 v[34:37], v[164:167], v[214:217], v[34:37]
	v_mfma_f32_16x16x32_bf16 v[26:29], v[172:175], v[214:217], v[26:29]
	v_mfma_f32_16x16x32_bf16 v[18:21], v[164:167], v[222:225], v[18:21]
	v_mfma_f32_16x16x32_bf16 v[10:13], v[172:175], v[222:225], v[10:13]
	v_mfma_f32_16x16x32_bf16 v[54:57], v[176:179], v[192:195], v[54:57]
	v_mfma_f32_16x16x32_bf16 v[46:49], v[184:187], v[192:195], v[46:49]
	v_mfma_f32_16x16x32_bf16 v[38:41], v[176:179], v[202:205], v[38:41]
	v_mfma_f32_16x16x32_bf16 v[30:33], v[184:187], v[202:205], v[30:33]
	v_mfma_f32_16x16x32_bf16 v[22:25], v[176:179], v[210:213], v[22:25]
	v_mfma_f32_16x16x32_bf16 v[14:17], v[184:187], v[210:213], v[14:17]
	v_mfma_f32_16x16x32_bf16 v[6:9], v[176:179], v[218:221], v[6:9]
	v_mfma_f32_16x16x32_bf16 v[2:5], v[184:187], v[218:221], v[2:5]
	v_mfma_f32_16x16x32_bf16 v[54:57], v[180:183], v[198:201], v[54:57]
	v_mfma_f32_16x16x32_bf16 v[46:49], v[188:191], v[198:201], v[46:49]
	v_mfma_f32_16x16x32_bf16 v[38:41], v[180:183], v[206:209], v[38:41]
	v_mfma_f32_16x16x32_bf16 v[30:33], v[188:191], v[206:209], v[30:33]
	v_mfma_f32_16x16x32_bf16 v[22:25], v[180:183], v[214:217], v[22:25]
	v_mfma_f32_16x16x32_bf16 v[14:17], v[188:191], v[214:217], v[14:17]
	v_mfma_f32_16x16x32_bf16 v[6:9], v[180:183], v[222:225], v[6:9]
	v_mfma_f32_16x16x32_bf16 v[2:5], v[188:191], v[222:225], v[2:5]
	s_setprio 0
	s_barrier
	s_add_i32 s57, 0, 0x18000
	v_add_u32_e32 v150, s57, v151
	s_add_i32 s58, 0, 0x1c000
	ds_read_b128 v[160:163], v150
	ds_read_b128 v[164:167], v150 offset:1024
	ds_read_b128 v[168:171], v150 offset:2048
	ds_read_b128 v[172:175], v150 offset:3072
	v_add_u32_e32 v150, s58, v151
	ds_read_b128 v[176:179], v150
	ds_read_b128 v[180:183], v150 offset:1024
	ds_read_b128 v[184:187], v150 offset:2048
	ds_read_b128 v[188:191], v150 offset:3072
	s_add_u32 s48, s48, 0x40000
	s_addc_u32 s49, s49, 0
	s_mov_b32 m0, s16
	v_lshl_add_u64 v[236:237], s[48:49], 0, v[140:141]
	ds_read_b128 v[192:195], v159 offset:32768
	ds_read_b128 v[198:201], v159 offset:33792
	ds_read_b128 v[202:205], v159 offset:34816
	ds_read_b128 v[206:209], v159 offset:35840
	ds_read_b128 v[210:213], v159 offset:36864
	ds_read_b128 v[214:217], v159 offset:37888
	ds_read_b128 v[218:221], v159 offset:38912
	ds_read_b128 v[222:225], v159 offset:39936
	global_load_lds_dwordx4 v[236:237], off
	v_lshl_add_u64 v[236:237], s[48:49], 0, v[136:137]
	s_mov_b32 m0, s17
	s_nop 0
	global_load_lds_dwordx4 v[236:237], off
	s_waitcnt vmcnt(8)
	s_waitcnt lgkmcnt(0)
	s_barrier
	s_setprio 1
	s_waitcnt lgkmcnt(0)
	v_mfma_f32_16x16x32_bf16 v[132:135], v[160:163], v[192:195], v[132:135]
	v_mfma_f32_16x16x32_bf16 v[128:131], v[168:171], v[192:195], v[128:131]
	v_mfma_f32_16x16x32_bf16 v[120:123], v[160:163], v[202:205], v[120:123]
	v_mfma_f32_16x16x32_bf16 v[112:115], v[168:171], v[202:205], v[112:115]
	v_mfma_f32_16x16x32_bf16 v[104:107], v[160:163], v[210:213], v[104:107]
	v_mfma_f32_16x16x32_bf16 v[96:99], v[168:171], v[210:213], v[96:99]
	v_mfma_f32_16x16x32_bf16 v[88:91], v[160:163], v[218:221], v[88:91]
	v_mfma_f32_16x16x32_bf16 v[74:77], v[168:171], v[218:221], v[74:77]
	v_mfma_f32_16x16x32_bf16 v[132:135], v[164:167], v[198:201], v[132:135]
	v_mfma_f32_16x16x32_bf16 v[128:131], v[172:175], v[198:201], v[128:131]
	v_mfma_f32_16x16x32_bf16 v[120:123], v[164:167], v[206:209], v[120:123]
	v_mfma_f32_16x16x32_bf16 v[112:115], v[172:175], v[206:209], v[112:115]
	v_mfma_f32_16x16x32_bf16 v[104:107], v[164:167], v[214:217], v[104:107]
	v_mfma_f32_16x16x32_bf16 v[96:99], v[172:175], v[214:217], v[96:99]
	v_mfma_f32_16x16x32_bf16 v[88:91], v[164:167], v[222:225], v[88:91]
	v_mfma_f32_16x16x32_bf16 v[74:77], v[172:175], v[222:225], v[74:77]
	v_mfma_f32_16x16x32_bf16 v[124:127], v[176:179], v[192:195], v[124:127]
	v_mfma_f32_16x16x32_bf16 v[116:119], v[184:187], v[192:195], v[116:119]
	v_mfma_f32_16x16x32_bf16 v[108:111], v[176:179], v[202:205], v[108:111]
	v_mfma_f32_16x16x32_bf16 v[100:103], v[184:187], v[202:205], v[100:103]
	v_mfma_f32_16x16x32_bf16 v[92:95], v[176:179], v[210:213], v[92:95]
	v_mfma_f32_16x16x32_bf16 v[84:87], v[184:187], v[210:213], v[84:87]
	v_mfma_f32_16x16x32_bf16 v[70:73], v[176:179], v[218:221], v[70:73]
	v_mfma_f32_16x16x32_bf16 v[66:69], v[184:187], v[218:221], v[66:69]
	v_mfma_f32_16x16x32_bf16 v[124:127], v[180:183], v[198:201], v[124:127]
	v_mfma_f32_16x16x32_bf16 v[116:119], v[188:191], v[198:201], v[116:119]
	v_mfma_f32_16x16x32_bf16 v[108:111], v[180:183], v[206:209], v[108:111]
	v_mfma_f32_16x16x32_bf16 v[100:103], v[188:191], v[206:209], v[100:103]
	v_mfma_f32_16x16x32_bf16 v[92:95], v[180:183], v[214:217], v[92:95]
	v_mfma_f32_16x16x32_bf16 v[84:87], v[188:191], v[214:217], v[84:87]
	v_mfma_f32_16x16x32_bf16 v[70:73], v[180:183], v[222:225], v[70:73]
	v_mfma_f32_16x16x32_bf16 v[66:69], v[188:191], v[222:225], v[66:69]
	s_setprio 0
	s_barrier
; #define PG8_STAGE(bufoff, gbase, voff) do { _Pragma("unroll") for (int _i = 0; _i < 2; ++_i) \
;         __builtin_amdgcn_global_load_lds((const unsigned*)((const char*)(gbase) + (voff)[_i]), (PG8_LAS unsigned*)(lds + (bufoff) + ldsw + _i * 8192), 16, 0, 0); } while (0)
; #define PG8_LDA(dst, b, h) do { _Pragma("unroll") for (int m = 0; m < 4; ++m) _Pragma("unroll") for (int k = 0; k < 2; ++k) dst[m][k] = *(const PG8_LAS bf16x8*)(lds + PG8_SA(b, h) + aoff + m * 2048 + k * 1024); } while (0)
; #define PG8_LDB(dst, b, h) do { _Pragma("unroll") for (int n = 0; n < 2; ++n) _Pragma("unroll") for (int k = 0; k < 2; ++k) dst[n][k] = *(const PG8_LAS bf16x8*)(lds + PG8_SB(b, h) + boff + n * 2048 + k * 1024); } while (0)
; template <class Epi, class Sched, bool ALIGN_EPI = false, bool SP2 = false>
; __device__ __forceinline__ void gemm_phase(PG8_LAS unsigned char* lds, const Gemm g, const Sched& S, const Epi& E) {
;     ...
;         for (int t = 0; t < nt; t += 2) {
;             const bool last = (t == nt - 2);
;             const char* a1 = cA + (size_t)(t + 1) * kstep;
;             const char* a2 = last ? nA : cA + (size_t)(t + 2) * kstep; const char* b2 = last ? nB : cB + (size_t)(t + 2) * kstep;
;             const char* a3 = a2 + kstep; const char* b3 = b2 + kstep;
;             if (last && has_next) S.a_ready(nxt);
;             if constexpr (SP2) {
;             PG8_LDB(B0, 0, 0); PG8_LDB(B1, 0, 1); PG8_SCHED; PG8_LDA(At, 0, 0); PG8_STAGE(PG8_SA(1, 1), a1 + hstepA, voffA);
;             PG8_WAIT_V(8); PG8_WAIT_L(0); PG8_BAR; PG8_MMA(0, 0, At, B0); PG8_MMA(0, 1, At, B1); PG8_BAR; PG8_SCHED;
;             PG8_LDA(At, 0, 1); PG8_STAGE(PG8_SB(0, 0), b2, voffB); PG8_STAGE(PG8_SB(0, 1), b2 + hstep, voffB); PG8_STAGE(PG8_SA(0, 0), a2, voffA);
;             PG8_WAIT_V(8); PG8_WAIT_L(0); PG8_BAR; PG8_MMA(1, 0, At, B0); PG8_MMA(1, 1, At, B1); PG8_BAR; PG8_SCHED;
;             PG8_LDB(B0, 1, 0); PG8_LDB(B1, 1, 1); PG8_SCHED; PG8_LDA(At, 1, 0); PG8_STAGE(PG8_SA(0, 1), a2 + hstepA, voffA);
;             PG8_WAIT_V(8); PG8_WAIT_L(0); PG8_BAR; PG8_MMA(0, 0, At, B0); PG8_MMA(0, 1, At, B1); PG8_BAR; PG8_SCHED;
;             PG8_LDA(At, 1, 1); PG8_STAGE(PG8_SB(1, 0), b3, voffB); PG8_STAGE(PG8_SB(1, 1), b3 + hstep, voffB); PG8_STAGE(PG8_SA(1, 0), a3, voffA);
;             PG8_WAIT_V(8); PG8_WAIT_L(0); PG8_BAR; PG8_MMA(1, 0, At, B0); PG8_MMA(1, 1, At, B1); PG8_BAR; PG8_SCHED;
	s_add_i32 s48, s57, s0
	v_lshl_add_u64 v[148:149], v[148:149], 0, s[26:27]
	s_mov_b32 m0, s48
	ds_read_b128 v[192:195], v159 offset:49152
	ds_read_b128 v[198:201], v159 offset:50176
	ds_read_b128 v[202:205], v159 offset:51200
	ds_read_b128 v[206:209], v159 offset:52224
	ds_read_b128 v[210:213], v159 offset:53248
	ds_read_b128 v[214:217], v159 offset:54272
	ds_read_b128 v[218:221], v159 offset:55296
	ds_read_b128 v[222:225], v159 offset:56320
	global_load_lds_dwordx4 v[148:149], off
	s_add_i32 m0, s48, 0x2000
	s_add_u32 s46, s46, 0x40080
	v_lshl_add_u64 v[148:149], v[152:153], 0, s[26:27]
	s_addc_u32 s47, s47, 0
	s_add_i32 s48, s58, s0
	global_load_lds_dwordx4 v[148:149], off
	v_lshl_add_u64 v[148:149], s[46:47], 0, v[138:139]
	s_mov_b32 m0, s48
	s_nop 0
	global_load_lds_dwordx4 v[148:149], off
	v_lshl_add_u64 v[148:149], s[46:47], 0, v[78:79]
	s_add_i32 m0, s48, 0x2000
	s_nop 0
	global_load_lds_dwordx4 v[148:149], off
	v_lshl_add_u64 v[148:149], v[156:157], 0, s[26:27]
	s_mov_b32 m0, s24
	s_nop 0
	global_load_lds_dwordx4 v[148:149], off
	v_lshl_add_u64 v[148:149], v[226:227], 0, s[26:27]
	s_mov_b32 m0, s25
	s_nop 0
	global_load_lds_dwordx4 v[148:149], off
	s_waitcnt vmcnt(8)
	s_waitcnt lgkmcnt(0)
	s_barrier
	s_setprio 1
	s_waitcnt lgkmcnt(0)
	v_mfma_f32_16x16x32_bf16 v[62:65], v[160:163], v[192:195], v[62:65]
	v_mfma_f32_16x16x32_bf16 v[58:61], v[168:171], v[192:195], v[58:61]
	v_mfma_f32_16x16x32_bf16 v[50:53], v[160:163], v[202:205], v[50:53]
	v_mfma_f32_16x16x32_bf16 v[42:45], v[168:171], v[202:205], v[42:45]
	v_mfma_f32_16x16x32_bf16 v[34:37], v[160:163], v[210:213], v[34:37]
	v_mfma_f32_16x16x32_bf16 v[26:29], v[168:171], v[210:213], v[26:29]
	v_mfma_f32_16x16x32_bf16 v[18:21], v[160:163], v[218:221], v[18:21]
	v_mfma_f32_16x16x32_bf16 v[10:13], v[168:171], v[218:221], v[10:13]
	v_mfma_f32_16x16x32_bf16 v[62:65], v[164:167], v[198:201], v[62:65]
	v_mfma_f32_16x16x32_bf16 v[58:61], v[172:175], v[198:201], v[58:61]
	v_mfma_f32_16x16x32_bf16 v[50:53], v[164:167], v[206:209], v[50:53]
	v_mfma_f32_16x16x32_bf16 v[42:45], v[172:175], v[206:209], v[42:45]
	v_mfma_f32_16x16x32_bf16 v[34:37], v[164:167], v[214:217], v[34:37]
	v_mfma_f32_16x16x32_bf16 v[26:29], v[172:175], v[214:217], v[26:29]
	v_mfma_f32_16x16x32_bf16 v[18:21], v[164:167], v[222:225], v[18:21]
	v_mfma_f32_16x16x32_bf16 v[10:13], v[172:175], v[222:225], v[10:13]
	v_mfma_f32_16x16x32_bf16 v[54:57], v[176:179], v[192:195], v[54:57]
	v_mfma_f32_16x16x32_bf16 v[46:49], v[184:187], v[192:195], v[46:49]
	v_mfma_f32_16x16x32_bf16 v[38:41], v[176:179], v[202:205], v[38:41]
	v_mfma_f32_16x16x32_bf16 v[30:33], v[184:187], v[202:205], v[30:33]
	v_mfma_f32_16x16x32_bf16 v[22:25], v[176:179], v[210:213], v[22:25]
	v_mfma_f32_16x16x32_bf16 v[14:17], v[184:187], v[210:213], v[14:17]
	v_mfma_f32_16x16x32_bf16 v[6:9], v[176:179], v[218:221], v[6:9]
	v_mfma_f32_16x16x32_bf16 v[2:5], v[184:187], v[218:221], v[2:5]
	v_mfma_f32_16x16x32_bf16 v[54:57], v[180:183], v[198:201], v[54:57]
	v_mfma_f32_16x16x32_bf16 v[46:49], v[188:191], v[198:201], v[46:49]
	v_mfma_f32_16x16x32_bf16 v[38:41], v[180:183], v[206:209], v[38:41]
	v_mfma_f32_16x16x32_bf16 v[30:33], v[188:191], v[206:209], v[30:33]
	v_mfma_f32_16x16x32_bf16 v[22:25], v[180:183], v[214:217], v[22:25]
	v_mfma_f32_16x16x32_bf16 v[14:17], v[188:191], v[214:217], v[14:17]
	v_mfma_f32_16x16x32_bf16 v[6:9], v[180:183], v[222:225], v[6:9]
	v_mfma_f32_16x16x32_bf16 v[2:5], v[188:191], v[222:225], v[2:5]
	s_setprio 0
	s_barrier
	s_add_i32 s56, s56, 2
	s_add_u32 s44, s44, 0x100
	s_addc_u32 s45, s45, 0
	s_add_u32 s54, s54, 0x100
	s_addc_u32 s55, s55, 0
	s_cmp_gt_u32 s56, 13
	s_cbranch_scc0 .LBB0_370
	s_and_b64 vcc, exec, s[8:9]
	s_cbranch_vccz .LBB0_373
	s_barrier

; #define PG8_STAGE(bufoff, gbase, voff) do { _Pragma("unroll") for (int _i = 0; _i < 2; ++_i) \
;         __builtin_amdgcn_global_load_lds((const unsigned*)((const char*)(gbase) + (voff)[_i]), (PG8_LAS unsigned*)(lds + (bufoff) + ldsw + _i * 8192), 16, 0, 0); } while (0)
; #define PG8_LDA(dst, b, h) do { _Pragma("unroll") for (int m = 0; m < 4; ++m) _Pragma("unroll") for (int k = 0; k < 2; ++k) dst[m][k] = *(const PG8_LAS bf16x8*)(lds + PG8_SA(b, h) + aoff + m * 2048 + k * 1024); } while (0)
; #define PG8_LDB(dst, b, h) do { _Pragma("unroll") for (int n = 0; n < 2; ++n) _Pragma("unroll") for (int k = 0; k < 2; ++k) dst[n][k] = *(const PG8_LAS bf16x8*)(lds + PG8_SB(b, h) + boff + n * 2048 + k * 1024); } while (0)
; #define PG8_MMA(ai, bj, At, Bt) do { __builtin_amdgcn_s_setprio(1); _Pragma("unroll") for (int m = 0; m < 4; ++m) _Pragma("unroll") for (int n = 0; n < 2; ++n) _Pragma("unroll") for (int k = 0; k < 2; ++k) \
;         acc[ai][bj][m][n] = __builtin_amdgcn_mfma_f32_16x16x32_bf16(Bt[n][k], At[m][k], acc[ai][bj][m][n], 0, 0, 0); __builtin_amdgcn_s_setprio(0); } while (0)
; #define PG8_WAIT_V(n) asm volatile("s_waitcnt vmcnt(" #n ")" ::: "memory")
; #define PG8_WAIT_L(n) asm volatile("s_waitcnt lgkmcnt(" #n ")" ::: "memory")
; template <class Epi, class Sched, bool ALIGN_EPI = false, bool SP2 = false>
; __device__ __forceinline__ void gemm_phase(PG8_LAS unsigned char* lds, const Gemm g, const Sched& S, const Epi& E) {
;     ...
;             const bool last = (t == nt - 2);
;             const char* a1 = cA + (size_t)(t + 1) * kstep;
;             const char* a2 = last ? nA : cA + (size_t)(t + 2) * kstep; const char* b2 = last ? nB : cB + (size_t)(t + 2) * kstep;
;             const char* a3 = a2 + kstep; const char* b3 = b2 + kstep;
;             if (last && has_next) S.a_ready(nxt);
;             if constexpr (SP2) {
;             PG8_LDB(B0, 0, 0); PG8_LDB(B1, 0, 1); PG8_SCHED; PG8_LDA(At, 0, 0); PG8_STAGE(PG8_SA(1, 1), a1 + hstepA, voffA);
;             PG8_WAIT_V(8); PG8_WAIT_L(0); PG8_BAR; PG8_MMA(0, 0, At, B0); PG8_MMA(0, 1, At, B1); PG8_BAR; PG8_SCHED;
;             PG8_LDA(At, 0, 1); PG8_STAGE(PG8_SB(0, 0), b2, voffB); PG8_STAGE(PG8_SB(0, 1), b2 + hstep, voffB); PG8_STAGE(PG8_SA(0, 0), a2, voffA);
;             PG8_WAIT_V(8); PG8_WAIT_L(0); PG8_BAR; PG8_MMA(1, 0, At, B0); PG8_MMA(1, 1, At, B1); PG8_BAR; PG8_SCHED;
.LBB0_527:
	s_add_i32 s89, s72, 2
	s_add_u32 s90, s42, 0x80
	s_addc_u32 s73, s43, 0
	s_add_i32 s92, 0, 0x10000
	s_cmp_eq_u32 s79, s72
	s_cselect_b32 s73, s7, s73
	s_cselect_b32 s72, s6, s90
	v_add_u32_e32 v150, s92, v151
	s_cselect_b32 s91, s71, s88
	s_cselect_b32 s90, s70, s87
	s_add_i32 s93, 0, 0x14000
	ds_read_b128 v[146:149], v150
	ds_read_b128 v[156:159], v150 offset:1024
	ds_read_b128 v[160:163], v150 offset:2048
	ds_read_b128 v[164:167], v150 offset:3072
	v_add_u32_e32 v150, s93, v151
	ds_read_b128 v[168:171], v150
	ds_read_b128 v[172:175], v150 offset:1024
	ds_read_b128 v[176:179], v150 offset:2048
	ds_read_b128 v[180:183], v150 offset:3072
	v_lshl_add_u64 v[218:219], s[42:43], 0, v[142:143]
	s_add_i32 m0, s25, 0xc000
	ds_read_b128 v[184:187], v155
	ds_read_b128 v[188:191], v155 offset:1024
	ds_read_b128 v[192:195], v155 offset:2048
	ds_read_b128 v[198:201], v155 offset:3072
	ds_read_b128 v[202:205], v155 offset:4096
	ds_read_b128 v[206:209], v155 offset:5120
	ds_read_b128 v[210:213], v155 offset:6144
	ds_read_b128 v[214:217], v155 offset:7168
	global_load_lds_dwordx4 v[218:219], off
	v_lshl_add_u64 v[218:219], s[42:43], 0, v[144:145]
	s_add_i32 m0, s25, 0xe000
	s_nop 0
	global_load_lds_dwordx4 v[218:219], off
	s_waitcnt vmcnt(8)
	s_waitcnt lgkmcnt(0)
	s_barrier
	s_setprio 1
	s_waitcnt lgkmcnt(0)
	v_mfma_f32_16x16x32_bf16 v[132:135], v[146:149], v[184:187], v[132:135]
	v_mfma_f32_16x16x32_bf16 v[128:131], v[160:163], v[184:187], v[128:131]
	v_mfma_f32_16x16x32_bf16 v[116:119], v[146:149], v[192:195], v[116:119]
	v_mfma_f32_16x16x32_bf16 v[112:115], v[160:163], v[192:195], v[112:115]
	v_mfma_f32_16x16x32_bf16 v[100:103], v[146:149], v[202:205], v[100:103]
	v_mfma_f32_16x16x32_bf16 v[96:99], v[160:163], v[202:205], v[96:99]
	v_mfma_f32_16x16x32_bf16 v[84:87], v[146:149], v[210:213], v[84:87]
	v_mfma_f32_16x16x32_bf16 v[74:77], v[160:163], v[210:213], v[74:77]
	v_mfma_f32_16x16x32_bf16 v[132:135], v[156:159], v[188:191], v[132:135]
	v_mfma_f32_16x16x32_bf16 v[128:131], v[164:167], v[188:191], v[128:131]
	v_mfma_f32_16x16x32_bf16 v[116:119], v[156:159], v[198:201], v[116:119]
	v_mfma_f32_16x16x32_bf16 v[112:115], v[164:167], v[198:201], v[112:115]
	v_mfma_f32_16x16x32_bf16 v[100:103], v[156:159], v[206:209], v[100:103]
	v_mfma_f32_16x16x32_bf16 v[96:99], v[164:167], v[206:209], v[96:99]
	v_mfma_f32_16x16x32_bf16 v[84:87], v[156:159], v[214:217], v[84:87]
	v_mfma_f32_16x16x32_bf16 v[74:77], v[164:167], v[214:217], v[74:77]
	v_mfma_f32_16x16x32_bf16 v[124:127], v[168:171], v[184:187], v[124:127]
	v_mfma_f32_16x16x32_bf16 v[120:123], v[176:179], v[184:187], v[120:123]
	v_mfma_f32_16x16x32_bf16 v[108:111], v[168:171], v[192:195], v[108:111]
	v_mfma_f32_16x16x32_bf16 v[104:107], v[176:179], v[192:195], v[104:107]
	v_mfma_f32_16x16x32_bf16 v[92:95], v[168:171], v[202:205], v[92:95]
	v_mfma_f32_16x16x32_bf16 v[88:91], v[176:179], v[202:205], v[88:91]
	v_mfma_f32_16x16x32_bf16 v[70:73], v[168:171], v[210:213], v[70:73]
	v_mfma_f32_16x16x32_bf16 v[66:69], v[176:179], v[210:213], v[66:69]
	v_mfma_f32_16x16x32_bf16 v[124:127], v[172:175], v[188:191], v[124:127]
	v_mfma_f32_16x16x32_bf16 v[120:123], v[180:183], v[188:191], v[120:123]
	v_mfma_f32_16x16x32_bf16 v[108:111], v[172:175], v[198:201], v[108:111]
	v_mfma_f32_16x16x32_bf16 v[104:107], v[180:183], v[198:201], v[104:107]
	v_mfma_f32_16x16x32_bf16 v[92:95], v[172:175], v[206:209], v[92:95]
	v_mfma_f32_16x16x32_bf16 v[88:91], v[180:183], v[206:209], v[88:91]
	v_mfma_f32_16x16x32_bf16 v[70:73], v[172:175], v[214:217], v[70:73]
	v_mfma_f32_16x16x32_bf16 v[66:69], v[180:183], v[214:217], v[66:69]
	s_setprio 0
	s_barrier
	s_add_i32 s92, s92, s21
	v_lshl_add_u64 v[218:219], s[90:91], 0, v[136:137]
	s_mov_b32 m0, s92
	ds_read_b128 v[184:187], v155 offset:16384
	ds_read_b128 v[188:191], v155 offset:17408
	ds_read_b128 v[192:195], v155 offset:18432
	ds_read_b128 v[198:201], v155 offset:19456
	ds_read_b128 v[202:205], v155 offset:20480
	ds_read_b128 v[206:209], v155 offset:21504
	ds_read_b128 v[210:213], v155 offset:22528
	ds_read_b128 v[214:217], v155 offset:23552
	global_load_lds_dwordx4 v[218:219], off
	s_add_i32 m0, s92, 0x2000
	v_lshl_add_u64 v[220:221], s[90:91], 0, v[140:141]
	s_add_u32 s90, s90, s0
	s_addc_u32 s91, s91, 0
	s_add_i32 s92, s93, s21
	global_load_lds_dwordx4 v[220:221], off
	v_lshl_add_u64 v[222:223], s[90:91], 0, v[136:137]
	s_mov_b32 m0, s92
	v_lshl_add_u64 v[224:225], s[90:91], 0, v[140:141]
	global_load_lds_dwordx4 v[222:223], off
	s_add_i32 m0, s92, 0x2000
	v_lshl_add_u64 v[226:227], s[72:73], 0, v[78:79]
	global_load_lds_dwordx4 v[224:225], off
	s_mov_b32 m0, s25
	v_lshl_add_u64 v[236:237], s[72:73], 0, v[138:139]
	global_load_lds_dwordx4 v[226:227], off
	s_mov_b32 m0, s37
	s_nop 0
	global_load_lds_dwordx4 v[236:237], off
	s_waitcnt vmcnt(8)
	s_waitcnt lgkmcnt(0)
	s_barrier
; #define PG8_STAGE(bufoff, gbase, voff) do { _Pragma("unroll") for (int _i = 0; _i < 2; ++_i) \
;         __builtin_amdgcn_global_load_lds((const unsigned*)((const char*)(gbase) + (voff)[_i]), (PG8_LAS unsigned*)(lds + (bufoff) + ldsw + _i * 8192), 16, 0, 0); } while (0)
; #define PG8_LDA(dst, b, h) do { _Pragma("unroll") for (int m = 0; m < 4; ++m) _Pragma("unroll") for (int k = 0; k < 2; ++k) dst[m][k] = *(const PG8_LAS bf16x8*)(lds + PG8_SA(b, h) + aoff + m * 2048 + k * 1024); } while (0)
; #define PG8_LDB(dst, b, h) do { _Pragma("unroll") for (int n = 0; n < 2; ++n) _Pragma("unroll") for (int k = 0; k < 2; ++k) dst[n][k] = *(const PG8_LAS bf16x8*)(lds + PG8_SB(b, h) + boff + n * 2048 + k * 1024); } while (0)
; #define PG8_MMA(ai, bj, At, Bt) do { __builtin_amdgcn_s_setprio(1); _Pragma("unroll") for (int m = 0; m < 4; ++m) _Pragma("unroll") for (int n = 0; n < 2; ++n) _Pragma("unroll") for (int k = 0; k < 2; ++k) \
;         acc[ai][bj][m][n] = __builtin_amdgcn_mfma_f32_16x16x32_bf16(Bt[n][k], At[m][k], acc[ai][bj][m][n], 0, 0, 0); __builtin_amdgcn_s_setprio(0); } while (0)
; #define PG8_WAIT_V(n) asm volatile("s_waitcnt vmcnt(" #n ")" ::: "memory")
; #define PG8_WAIT_L(n) asm volatile("s_waitcnt lgkmcnt(" #n ")" ::: "memory")
; #define PG8_BAR __builtin_amdgcn_s_barrier()
; #define PG8_SCHED __builtin_amdgcn_sched_barrier(0)
; template <class Epi, class Sched, bool ALIGN_EPI = false, bool SP2 = false>
; __device__ __forceinline__ void gemm_phase(PG8_LAS unsigned char* lds, const Gemm g, const Sched& S, const Epi& E) {
;     ...
;             PG8_WAIT_V(8); PG8_WAIT_L(0); PG8_BAR; PG8_MMA(1, 0, At, B0); PG8_MMA(1, 1, At, B1); PG8_BAR; PG8_SCHED;
;             PG8_LDB(B0, 1, 0); PG8_LDB(B1, 1, 1); PG8_SCHED; PG8_LDA(At, 1, 0); PG8_STAGE(PG8_SA(0, 1), a2 + hstepA, voffA);
;             PG8_WAIT_V(8); PG8_WAIT_L(0); PG8_BAR; PG8_MMA(0, 0, At, B0); PG8_MMA(0, 1, At, B1); PG8_BAR; PG8_SCHED;
	s_setprio 1
	s_waitcnt lgkmcnt(0)
	v_mfma_f32_16x16x32_bf16 v[62:65], v[146:149], v[184:187], v[62:65]
	v_mfma_f32_16x16x32_bf16 v[58:61], v[160:163], v[184:187], v[58:61]
	v_mfma_f32_16x16x32_bf16 v[46:49], v[146:149], v[192:195], v[46:49]
	v_mfma_f32_16x16x32_bf16 v[42:45], v[160:163], v[192:195], v[42:45]
	v_mfma_f32_16x16x32_bf16 v[30:33], v[146:149], v[202:205], v[30:33]
	v_mfma_f32_16x16x32_bf16 v[26:29], v[160:163], v[202:205], v[26:29]
	v_mfma_f32_16x16x32_bf16 v[14:17], v[146:149], v[210:213], v[14:17]
	v_mfma_f32_16x16x32_bf16 v[10:13], v[160:163], v[210:213], v[10:13]
	v_mfma_f32_16x16x32_bf16 v[62:65], v[156:159], v[188:191], v[62:65]
	v_mfma_f32_16x16x32_bf16 v[58:61], v[164:167], v[188:191], v[58:61]
	v_mfma_f32_16x16x32_bf16 v[46:49], v[156:159], v[198:201], v[46:49]
	v_mfma_f32_16x16x32_bf16 v[42:45], v[164:167], v[198:201], v[42:45]
	v_mfma_f32_16x16x32_bf16 v[30:33], v[156:159], v[206:209], v[30:33]
	v_mfma_f32_16x16x32_bf16 v[26:29], v[164:167], v[206:209], v[26:29]
	v_mfma_f32_16x16x32_bf16 v[14:17], v[156:159], v[214:217], v[14:17]
	v_mfma_f32_16x16x32_bf16 v[10:13], v[164:167], v[214:217], v[10:13]
	v_mfma_f32_16x16x32_bf16 v[54:57], v[168:171], v[184:187], v[54:57]
	v_mfma_f32_16x16x32_bf16 v[50:53], v[176:179], v[184:187], v[50:53]
	v_mfma_f32_16x16x32_bf16 v[38:41], v[168:171], v[192:195], v[38:41]
	v_mfma_f32_16x16x32_bf16 v[34:37], v[176:179], v[192:195], v[34:37]
	v_mfma_f32_16x16x32_bf16 v[22:25], v[168:171], v[202:205], v[22:25]
	v_mfma_f32_16x16x32_bf16 v[18:21], v[176:179], v[202:205], v[18:21]
	v_mfma_f32_16x16x32_bf16 v[6:9], v[168:171], v[210:213], v[6:9]
	v_mfma_f32_16x16x32_bf16 v[2:5], v[176:179], v[210:213], v[2:5]
	v_mfma_f32_16x16x32_bf16 v[54:57], v[172:175], v[188:191], v[54:57]
	v_mfma_f32_16x16x32_bf16 v[50:53], v[180:183], v[188:191], v[50:53]
	v_mfma_f32_16x16x32_bf16 v[38:41], v[172:175], v[198:201], v[38:41]
	v_mfma_f32_16x16x32_bf16 v[34:37], v[180:183], v[198:201], v[34:37]
	v_mfma_f32_16x16x32_bf16 v[22:25], v[172:175], v[206:209], v[22:25]
	v_mfma_f32_16x16x32_bf16 v[18:21], v[180:183], v[206:209], v[18:21]
	v_mfma_f32_16x16x32_bf16 v[6:9], v[172:175], v[214:217], v[6:9]
	v_mfma_f32_16x16x32_bf16 v[2:5], v[180:183], v[214:217], v[2:5]
	s_setprio 0
	s_barrier
	s_add_i32 s90, 0, 0x18000
	v_add_u32_e32 v150, s90, v151
	s_add_i32 s91, 0, 0x1c000
	ds_read_b128 v[146:149], v150
	ds_read_b128 v[156:159], v150 offset:1024
	ds_read_b128 v[160:163], v150 offset:2048
	ds_read_b128 v[164:167], v150 offset:3072
	v_add_u32_e32 v150, s91, v151
	ds_read_b128 v[168:171], v150
	ds_read_b128 v[172:175], v150 offset:1024
	ds_read_b128 v[176:179], v150 offset:2048
	ds_read_b128 v[180:183], v150 offset:3072
	s_add_u32 s72, s72, s0
	s_addc_u32 s73, s73, 0
	s_mov_b32 m0, s74
	v_lshl_add_u64 v[238:239], s[72:73], 0, v[78:79]
	ds_read_b128 v[184:187], v155 offset:32768
	ds_read_b128 v[188:191], v155 offset:33792
	ds_read_b128 v[192:195], v155 offset:34816
	ds_read_b128 v[198:201], v155 offset:35840
	ds_read_b128 v[202:205], v155 offset:36864
	ds_read_b128 v[206:209], v155 offset:37888
	ds_read_b128 v[210:213], v155 offset:38912
	ds_read_b128 v[214:217], v155 offset:39936
	global_load_lds_dwordx4 v[238:239], off
	v_lshl_add_u64 v[238:239], s[72:73], 0, v[138:139]
	s_mov_b32 m0, s75
	s_nop 0
	global_load_lds_dwordx4 v[238:239], off
	s_waitcnt vmcnt(8)
	s_waitcnt lgkmcnt(0)
	s_barrier
	s_setprio 1
	s_waitcnt lgkmcnt(0)
	v_mfma_f32_16x16x32_bf16 v[132:135], v[146:149], v[184:187], v[132:135]
	v_mfma_f32_16x16x32_bf16 v[128:131], v[160:163], v[184:187], v[128:131]
	v_mfma_f32_16x16x32_bf16 v[116:119], v[146:149], v[192:195], v[116:119]
	v_mfma_f32_16x16x32_bf16 v[112:115], v[160:163], v[192:195], v[112:115]
	v_mfma_f32_16x16x32_bf16 v[100:103], v[146:149], v[202:205], v[100:103]
	v_mfma_f32_16x16x32_bf16 v[96:99], v[160:163], v[202:205], v[96:99]
	v_mfma_f32_16x16x32_bf16 v[84:87], v[146:149], v[210:213], v[84:87]
	v_mfma_f32_16x16x32_bf16 v[74:77], v[160:163], v[210:213], v[74:77]
	v_mfma_f32_16x16x32_bf16 v[132:135], v[156:159], v[188:191], v[132:135]
	v_mfma_f32_16x16x32_bf16 v[128:131], v[164:167], v[188:191], v[128:131]
	v_mfma_f32_16x16x32_bf16 v[116:119], v[156:159], v[198:201], v[116:119]
	v_mfma_f32_16x16x32_bf16 v[112:115], v[164:167], v[198:201], v[112:115]
	v_mfma_f32_16x16x32_bf16 v[100:103], v[156:159], v[206:209], v[100:103]
	v_mfma_f32_16x16x32_bf16 v[96:99], v[164:167], v[206:209], v[96:99]
	v_mfma_f32_16x16x32_bf16 v[84:87], v[156:159], v[214:217], v[84:87]
	v_mfma_f32_16x16x32_bf16 v[74:77], v[164:167], v[214:217], v[74:77]
	v_mfma_f32_16x16x32_bf16 v[124:127], v[168:171], v[184:187], v[124:127]
	v_mfma_f32_16x16x32_bf16 v[120:123], v[176:179], v[184:187], v[120:123]
	v_mfma_f32_16x16x32_bf16 v[108:111], v[168:171], v[192:195], v[108:111]
	v_mfma_f32_16x16x32_bf16 v[104:107], v[176:179], v[192:195], v[104:107]
	v_mfma_f32_16x16x32_bf16 v[92:95], v[168:171], v[202:205], v[92:95]
	v_mfma_f32_16x16x32_bf16 v[88:91], v[176:179], v[202:205], v[88:91]
	v_mfma_f32_16x16x32_bf16 v[70:73], v[168:171], v[210:213], v[70:73]
	v_mfma_f32_16x16x32_bf16 v[66:69], v[176:179], v[210:213], v[66:69]
	v_mfma_f32_16x16x32_bf16 v[124:127], v[172:175], v[188:191], v[124:127]
	v_mfma_f32_16x16x32_bf16 v[120:123], v[180:183], v[188:191], v[120:123]
	v_mfma_f32_16x16x32_bf16 v[108:111], v[172:175], v[198:201], v[108:111]
	v_mfma_f32_16x16x32_bf16 v[104:107], v[180:183], v[198:201], v[104:107]
	v_mfma_f32_16x16x32_bf16 v[92:95], v[172:175], v[206:209], v[92:95]
	v_mfma_f32_16x16x32_bf16 v[88:91], v[180:183], v[206:209], v[88:91]
	v_mfma_f32_16x16x32_bf16 v[70:73], v[172:175], v[214:217], v[70:73]
	v_mfma_f32_16x16x32_bf16 v[66:69], v[180:183], v[214:217], v[66:69]
	s_setprio 0
	s_barrier
; #define PG8_STAGE(bufoff, gbase, voff) do { _Pragma("unroll") for (int _i = 0; _i < 2; ++_i) \
;         __builtin_amdgcn_global_load_lds((const unsigned*)((const char*)(gbase) + (voff)[_i]), (PG8_LAS unsigned*)(lds + (bufoff) + ldsw + _i * 8192), 16, 0, 0); } while (0)
; #define PG8_LDA(dst, b, h) do { _Pragma("unroll") for (int m = 0; m < 4; ++m) _Pragma("unroll") for (int k = 0; k < 2; ++k) dst[m][k] = *(const PG8_LAS bf16x8*)(lds + PG8_SA(b, h) + aoff + m * 2048 + k * 1024); } while (0)
; #define PG8_LDB(dst, b, h) do { _Pragma("unroll") for (int n = 0; n < 2; ++n) _Pragma("unroll") for (int k = 0; k < 2; ++k) dst[n][k] = *(const PG8_LAS bf16x8*)(lds + PG8_SB(b, h) + boff + n * 2048 + k * 1024); } while (0)
; template <class Epi, class Sched, bool ALIGN_EPI = false, bool SP2 = false>
; __device__ __forceinline__ void gemm_phase(PG8_LAS unsigned char* lds, const Gemm g, const Sched& S, const Epi& E) {
;     ...
;         for (int t = 0; t < nt; t += 2) {
;             const bool last = (t == nt - 2);
;             const char* a1 = cA + (size_t)(t + 1) * kstep;
;             const char* a2 = last ? nA : cA + (size_t)(t + 2) * kstep; const char* b2 = last ? nB : cB + (size_t)(t + 2) * kstep;
;             const char* a3 = a2 + kstep; const char* b3 = b2 + kstep;
;             if (last && has_next) S.a_ready(nxt);
;             if constexpr (SP2) {
;             PG8_LDB(B0, 0, 0); PG8_LDB(B1, 0, 1); PG8_SCHED; PG8_LDA(At, 0, 0); PG8_STAGE(PG8_SA(1, 1), a1 + hstepA, voffA);
;             PG8_WAIT_V(8); PG8_WAIT_L(0); PG8_BAR; PG8_MMA(0, 0, At, B0); PG8_MMA(0, 1, At, B1); PG8_BAR; PG8_SCHED;
;             PG8_LDA(At, 0, 1); PG8_STAGE(PG8_SB(0, 0), b2, voffB); PG8_STAGE(PG8_SB(0, 1), b2 + hstep, voffB); PG8_STAGE(PG8_SA(0, 0), a2, voffA);
;             PG8_WAIT_V(8); PG8_WAIT_L(0); PG8_BAR; PG8_MMA(1, 0, At, B0); PG8_MMA(1, 1, At, B1); PG8_BAR; PG8_SCHED;
;             PG8_LDB(B0, 1, 0); PG8_LDB(B1, 1, 1); PG8_SCHED; PG8_LDA(At, 1, 0); PG8_STAGE(PG8_SA(0, 1), a2 + hstepA, voffA);
;             PG8_WAIT_V(8); PG8_WAIT_L(0); PG8_BAR; PG8_MMA(0, 0, At, B0); PG8_MMA(0, 1, At, B1); PG8_BAR; PG8_SCHED;
;             PG8_LDA(At, 1, 1); PG8_STAGE(PG8_SB(1, 0), b3, voffB); PG8_STAGE(PG8_SB(1, 1), b3 + hstep, voffB); PG8_STAGE(PG8_SA(1, 0), a3, voffA);
;             PG8_WAIT_V(8); PG8_WAIT_L(0); PG8_BAR; PG8_MMA(1, 0, At, B0); PG8_MMA(1, 1, At, B1); PG8_BAR; PG8_SCHED;
	s_add_i32 s72, s90, s21
	v_lshl_add_u64 v[218:219], v[218:219], 0, s[26:27]
	s_mov_b32 m0, s72
	ds_read_b128 v[184:187], v155 offset:49152
	ds_read_b128 v[188:191], v155 offset:50176
	ds_read_b128 v[192:195], v155 offset:51200
	ds_read_b128 v[198:201], v155 offset:52224
	ds_read_b128 v[202:205], v155 offset:53248
	ds_read_b128 v[206:209], v155 offset:54272
	ds_read_b128 v[210:213], v155 offset:55296
	ds_read_b128 v[214:217], v155 offset:56320
	global_load_lds_dwordx4 v[218:219], off
	v_lshl_add_u64 v[218:219], v[220:221], 0, s[26:27]
	s_add_i32 m0, s72, 0x2000
	s_add_i32 s72, s91, s21
	global_load_lds_dwordx4 v[218:219], off
	v_lshl_add_u64 v[218:219], v[222:223], 0, s[26:27]
	s_mov_b32 m0, s72
	s_nop 0
	global_load_lds_dwordx4 v[218:219], off
	v_lshl_add_u64 v[218:219], v[224:225], 0, s[26:27]
	s_add_i32 m0, s72, 0x2000
	s_nop 0
	global_load_lds_dwordx4 v[218:219], off
	v_lshl_add_u64 v[218:219], v[226:227], 0, s[26:27]
	s_mov_b32 m0, s76
	s_nop 0
	global_load_lds_dwordx4 v[218:219], off
	v_lshl_add_u64 v[218:219], v[236:237], 0, s[26:27]
	s_mov_b32 m0, s77
	s_nop 0
	global_load_lds_dwordx4 v[218:219], off
	s_waitcnt vmcnt(8)
	s_waitcnt lgkmcnt(0)
	s_barrier
	s_setprio 1
	s_waitcnt lgkmcnt(0)
	v_mfma_f32_16x16x32_bf16 v[62:65], v[146:149], v[184:187], v[62:65]
	v_mfma_f32_16x16x32_bf16 v[58:61], v[160:163], v[184:187], v[58:61]
	v_mfma_f32_16x16x32_bf16 v[46:49], v[146:149], v[192:195], v[46:49]
	v_mfma_f32_16x16x32_bf16 v[42:45], v[160:163], v[192:195], v[42:45]
	v_mfma_f32_16x16x32_bf16 v[30:33], v[146:149], v[202:205], v[30:33]
	v_mfma_f32_16x16x32_bf16 v[26:29], v[160:163], v[202:205], v[26:29]
	v_mfma_f32_16x16x32_bf16 v[14:17], v[146:149], v[210:213], v[14:17]
	v_mfma_f32_16x16x32_bf16 v[10:13], v[160:163], v[210:213], v[10:13]
	v_mfma_f32_16x16x32_bf16 v[62:65], v[156:159], v[188:191], v[62:65]
	v_mfma_f32_16x16x32_bf16 v[58:61], v[164:167], v[188:191], v[58:61]
	v_mfma_f32_16x16x32_bf16 v[46:49], v[156:159], v[198:201], v[46:49]
	v_mfma_f32_16x16x32_bf16 v[42:45], v[164:167], v[198:201], v[42:45]
	v_mfma_f32_16x16x32_bf16 v[30:33], v[156:159], v[206:209], v[30:33]
	v_mfma_f32_16x16x32_bf16 v[26:29], v[164:167], v[206:209], v[26:29]
	v_mfma_f32_16x16x32_bf16 v[14:17], v[156:159], v[214:217], v[14:17]
	v_mfma_f32_16x16x32_bf16 v[10:13], v[164:167], v[214:217], v[10:13]
	v_mfma_f32_16x16x32_bf16 v[54:57], v[168:171], v[184:187], v[54:57]
	v_mfma_f32_16x16x32_bf16 v[50:53], v[176:179], v[184:187], v[50:53]
	v_mfma_f32_16x16x32_bf16 v[38:41], v[168:171], v[192:195], v[38:41]
	v_mfma_f32_16x16x32_bf16 v[34:37], v[176:179], v[192:195], v[34:37]
	v_mfma_f32_16x16x32_bf16 v[22:25], v[168:171], v[202:205], v[22:25]
	v_mfma_f32_16x16x32_bf16 v[18:21], v[176:179], v[202:205], v[18:21]
	v_mfma_f32_16x16x32_bf16 v[6:9], v[168:171], v[210:213], v[6:9]
	v_mfma_f32_16x16x32_bf16 v[2:5], v[176:179], v[210:213], v[2:5]
	v_mfma_f32_16x16x32_bf16 v[54:57], v[172:175], v[188:191], v[54:57]
	v_mfma_f32_16x16x32_bf16 v[50:53], v[180:183], v[188:191], v[50:53]
	v_mfma_f32_16x16x32_bf16 v[38:41], v[172:175], v[198:201], v[38:41]
	v_mfma_f32_16x16x32_bf16 v[34:37], v[180:183], v[198:201], v[34:37]
	v_mfma_f32_16x16x32_bf16 v[22:25], v[172:175], v[206:209], v[22:25]
	v_mfma_f32_16x16x32_bf16 v[18:21], v[180:183], v[206:209], v[18:21]
	v_mfma_f32_16x16x32_bf16 v[6:9], v[172:175], v[214:217], v[6:9]
	v_mfma_f32_16x16x32_bf16 v[2:5], v[180:183], v[214:217], v[2:5]
	s_setprio 0
	s_barrier
	s_add_u32 s42, s42, 0x100
	s_addc_u32 s43, s43, 0
	s_add_u32 s87, s87, 0x100
	s_addc_u32 s88, s88, 0
	s_cmp_ge_u32 s89, s78
	s_mov_b32 s72, s89
	s_cbranch_scc0 .LBB0_527
	s_and_b64 vcc, exec, s[64:65]
	s_cbranch_vccz .LBB0_530
	s_barrier

; #define PG8_STAGE(bufoff, gbase, voff) do { _Pragma("unroll") for (int _i = 0; _i < 2; ++_i) \
;         __builtin_amdgcn_global_load_lds((const unsigned*)((const char*)(gbase) + (voff)[_i]), (PG8_LAS unsigned*)(lds + (bufoff) + ldsw + _i * 8192), 16, 0, 0); } while (0)
; #define PG8_LDA(dst, b, h) do { _Pragma("unroll") for (int m = 0; m < 4; ++m) _Pragma("unroll") for (int k = 0; k < 2; ++k) dst[m][k] = *(const PG8_LAS bf16x8*)(lds + PG8_SA(b, h) + aoff + m * 2048 + k * 1024); } while (0)
; #define PG8_LDB(dst, b, h) do { _Pragma("unroll") for (int n = 0; n < 2; ++n) _Pragma("unroll") for (int k = 0; k < 2; ++k) dst[n][k] = *(const PG8_LAS bf16x8*)(lds + PG8_SB(b, h) + boff + n * 2048 + k * 1024); } while (0)
; #define PG8_MMA(ai, bj, At, Bt) do { __builtin_amdgcn_s_setprio(1); _Pragma("unroll") for (int m = 0; m < 4; ++m) _Pragma("unroll") for (int n = 0; n < 2; ++n) _Pragma("unroll") for (int k = 0; k < 2; ++k) \
;         acc[ai][bj][m][n] = __builtin_amdgcn_mfma_f32_16x16x32_bf16(Bt[n][k], At[m][k], acc[ai][bj][m][n], 0, 0, 0); __builtin_amdgcn_s_setprio(0); } while (0)
; #define PG8_WAIT_V(n) asm volatile("s_waitcnt vmcnt(" #n ")" ::: "memory")
; #define PG8_WAIT_L(n) asm volatile("s_waitcnt lgkmcnt(" #n ")" ::: "memory")
; template <class Epi, class Sched, bool ALIGN_EPI = false, bool SP2 = false>
; __device__ __forceinline__ void gemm_phase(PG8_LAS unsigned char* lds, const Gemm g, const Sched& S, const Epi& E) {
;     ...
;             const bool last = (t == nt - 2);
;             const char* a1 = cA + (size_t)(t + 1) * kstep;
;             const char* a2 = last ? nA : cA + (size_t)(t + 2) * kstep; const char* b2 = last ? nB : cB + (size_t)(t + 2) * kstep;
;             const char* a3 = a2 + kstep; const char* b3 = b2 + kstep;
;             if (last && has_next) S.a_ready(nxt);
;             if constexpr (SP2) {
;             PG8_LDB(B0, 0, 0); PG8_LDB(B1, 0, 1); PG8_SCHED; PG8_LDA(At, 0, 0); PG8_STAGE(PG8_SA(1, 1), a1 + hstepA, voffA);
;             PG8_WAIT_V(8); PG8_WAIT_L(0); PG8_BAR; PG8_MMA(0, 0, At, B0); PG8_MMA(0, 1, At, B1); PG8_BAR; PG8_SCHED;
;             PG8_LDA(At, 0, 1); PG8_STAGE(PG8_SB(0, 0), b2, voffB); PG8_STAGE(PG8_SB(0, 1), b2 + hstep, voffB); PG8_STAGE(PG8_SA(0, 0), a2, voffA);
;             PG8_WAIT_V(8); PG8_WAIT_L(0); PG8_BAR; PG8_MMA(1, 0, At, B0); PG8_MMA(1, 1, At, B1); PG8_BAR; PG8_SCHED;
.LBB0_600:
	s_add_i32 s66, s48, 2
	s_add_u32 s67, s46, 0x80
	s_addc_u32 s49, s47, 0
	s_add_i32 s70, 0, 0x10000
	s_cmp_eq_u32 s62, s48
	s_cselect_b32 s49, s7, s49
	s_cselect_b32 s48, s6, s67
	s_cselect_b32 s69, s21, s19
	s_cselect_b32 s68, s20, s5
	s_add_i32 s67, 0, 0x14000
	v_add_u32_e32 v140, s70, v243
	v_add_u32_e32 v156, s67, v243
	ds_read_b128 v[120:123], v140
	ds_read_b128 v[132:135], v140 offset:1024
	ds_read_b128 v[136:139], v140 offset:2048
	ds_read_b128 v[140:143], v140 offset:3072
	ds_read_b128 v[144:147], v156
	ds_read_b128 v[148:151], v156 offset:1024
	ds_read_b128 v[152:155], v156 offset:2048
	ds_read_b128 v[156:159], v156 offset:3072
	v_lshl_add_u64 v[212:213], s[46:47], 0, v[204:205]
	s_add_i32 m0, s55, 0xc000
	ds_read_b128 v[160:163], v247
	ds_read_b128 v[164:167], v247 offset:1024
	ds_read_b128 v[168:171], v247 offset:2048
	ds_read_b128 v[176:179], v247 offset:3072
	ds_read_b128 v[184:187], v247 offset:4096
	ds_read_b128 v[188:191], v247 offset:5120
	ds_read_b128 v[192:195], v247 offset:6144
	ds_read_b128 v[208:211], v247 offset:7168
	global_load_lds_dwordx4 v[212:213], off
	v_lshl_add_u64 v[212:213], s[46:47], 0, v[206:207]
	s_add_i32 m0, s55, 0xe000
	s_nop 0
	global_load_lds_dwordx4 v[212:213], off
	s_waitcnt vmcnt(8)
	s_waitcnt lgkmcnt(0)
	s_barrier
	s_setprio 1
	s_waitcnt lgkmcnt(0)
	v_mfma_f32_16x16x32_bf16 v[180:183], v[120:123], v[160:163], v[180:183]
	v_mfma_f32_16x16x32_bf16 v[172:175], v[136:139], v[160:163], v[172:175]
	v_mfma_f32_16x16x32_bf16 v[116:119], v[120:123], v[168:171], v[116:119]
	v_mfma_f32_16x16x32_bf16 v[112:115], v[136:139], v[168:171], v[112:115]
	v_mfma_f32_16x16x32_bf16 v[100:103], v[120:123], v[184:187], v[100:103]
	v_mfma_f32_16x16x32_bf16 v[96:99], v[136:139], v[184:187], v[96:99]
	v_mfma_f32_16x16x32_bf16 v[84:87], v[120:123], v[192:195], v[84:87]
	v_mfma_f32_16x16x32_bf16 v[74:77], v[136:139], v[192:195], v[74:77]
	v_mfma_f32_16x16x32_bf16 v[180:183], v[132:135], v[164:167], v[180:183]
	v_mfma_f32_16x16x32_bf16 v[172:175], v[140:143], v[164:167], v[172:175]
	v_mfma_f32_16x16x32_bf16 v[116:119], v[132:135], v[176:179], v[116:119]
	v_mfma_f32_16x16x32_bf16 v[112:115], v[140:143], v[176:179], v[112:115]
	v_mfma_f32_16x16x32_bf16 v[100:103], v[132:135], v[188:191], v[100:103]
	v_mfma_f32_16x16x32_bf16 v[96:99], v[140:143], v[188:191], v[96:99]
	v_mfma_f32_16x16x32_bf16 v[84:87], v[132:135], v[208:211], v[84:87]
	v_mfma_f32_16x16x32_bf16 v[74:77], v[140:143], v[208:211], v[74:77]
	v_mfma_f32_16x16x32_bf16 v[128:131], v[144:147], v[160:163], v[128:131]
	v_mfma_f32_16x16x32_bf16 v[124:127], v[152:155], v[160:163], v[124:127]
	v_mfma_f32_16x16x32_bf16 v[108:111], v[144:147], v[168:171], v[108:111]
	v_mfma_f32_16x16x32_bf16 v[104:107], v[152:155], v[168:171], v[104:107]
	v_mfma_f32_16x16x32_bf16 v[92:95], v[144:147], v[184:187], v[92:95]
	v_mfma_f32_16x16x32_bf16 v[88:91], v[152:155], v[184:187], v[88:91]
	v_mfma_f32_16x16x32_bf16 v[70:73], v[144:147], v[192:195], v[70:73]
	v_mfma_f32_16x16x32_bf16 v[66:69], v[152:155], v[192:195], v[66:69]
	v_mfma_f32_16x16x32_bf16 v[128:131], v[148:151], v[164:167], v[128:131]
	v_mfma_f32_16x16x32_bf16 v[124:127], v[156:159], v[164:167], v[124:127]
	v_mfma_f32_16x16x32_bf16 v[108:111], v[148:151], v[176:179], v[108:111]
	v_mfma_f32_16x16x32_bf16 v[104:107], v[156:159], v[176:179], v[104:107]
	v_mfma_f32_16x16x32_bf16 v[92:95], v[148:151], v[188:191], v[92:95]
	v_mfma_f32_16x16x32_bf16 v[88:91], v[156:159], v[188:191], v[88:91]
	v_mfma_f32_16x16x32_bf16 v[70:73], v[148:151], v[208:211], v[70:73]
	v_mfma_f32_16x16x32_bf16 v[66:69], v[156:159], v[208:211], v[66:69]
	s_setprio 0
	s_barrier
	s_add_i32 s70, s70, s54
	v_lshl_add_u64 v[212:213], s[68:69], 0, v[200:201]
	s_mov_b32 m0, s70
	ds_read_b128 v[160:163], v247 offset:16384
	ds_read_b128 v[164:167], v247 offset:17408
	ds_read_b128 v[168:171], v247 offset:18432
	ds_read_b128 v[176:179], v247 offset:19456
	ds_read_b128 v[184:187], v247 offset:20480
	ds_read_b128 v[188:191], v247 offset:21504
	ds_read_b128 v[192:195], v247 offset:22528
	ds_read_b128 v[208:211], v247 offset:23552
	global_load_lds_dwordx4 v[212:213], off
	s_add_i32 m0, s70, 0x2000
	v_lshl_add_u64 v[214:215], s[68:69], 0, v[78:79]
	s_add_u32 s68, s68, s25
	s_addc_u32 s69, s69, 0
	s_add_i32 s67, s67, s54
	global_load_lds_dwordx4 v[214:215], off
	v_lshl_add_u64 v[216:217], s[68:69], 0, v[200:201]
	s_mov_b32 m0, s67
	v_lshl_add_u64 v[218:219], s[68:69], 0, v[78:79]
	global_load_lds_dwordx4 v[216:217], off
	s_add_i32 m0, s67, 0x2000
	v_lshl_add_u64 v[220:221], s[48:49], 0, v[202:203]
	global_load_lds_dwordx4 v[218:219], off
	s_mov_b32 m0, s55
	v_lshl_add_u64 v[222:223], s[48:49], 0, v[198:199]
	global_load_lds_dwordx4 v[220:221], off
	s_mov_b32 m0, s56
	s_nop 0
	global_load_lds_dwordx4 v[222:223], off
	s_waitcnt vmcnt(8)
	s_waitcnt lgkmcnt(0)
	s_barrier
; #define PG8_STAGE(bufoff, gbase, voff) do { _Pragma("unroll") for (int _i = 0; _i < 2; ++_i) \
;         __builtin_amdgcn_global_load_lds((const unsigned*)((const char*)(gbase) + (voff)[_i]), (PG8_LAS unsigned*)(lds + (bufoff) + ldsw + _i * 8192), 16, 0, 0); } while (0)
; #define PG8_LDA(dst, b, h) do { _Pragma("unroll") for (int m = 0; m < 4; ++m) _Pragma("unroll") for (int k = 0; k < 2; ++k) dst[m][k] = *(const PG8_LAS bf16x8*)(lds + PG8_SA(b, h) + aoff + m * 2048 + k * 1024); } while (0)
; #define PG8_LDB(dst, b, h) do { _Pragma("unroll") for (int n = 0; n < 2; ++n) _Pragma("unroll") for (int k = 0; k < 2; ++k) dst[n][k] = *(const PG8_LAS bf16x8*)(lds + PG8_SB(b, h) + boff + n * 2048 + k * 1024); } while (0)
; #define PG8_MMA(ai, bj, At, Bt) do { __builtin_amdgcn_s_setprio(1); _Pragma("unroll") for (int m = 0; m < 4; ++m) _Pragma("unroll") for (int n = 0; n < 2; ++n) _Pragma("unroll") for (int k = 0; k < 2; ++k) \
;         acc[ai][bj][m][n] = __builtin_amdgcn_mfma_f32_16x16x32_bf16(Bt[n][k], At[m][k], acc[ai][bj][m][n], 0, 0, 0); __builtin_amdgcn_s_setprio(0); } while (0)
; #define PG8_WAIT_V(n) asm volatile("s_waitcnt vmcnt(" #n ")" ::: "memory")
; #define PG8_WAIT_L(n) asm volatile("s_waitcnt lgkmcnt(" #n ")" ::: "memory")
; #define PG8_BAR __builtin_amdgcn_s_barrier()
; #define PG8_SCHED __builtin_amdgcn_sched_barrier(0)
; template <class Epi, class Sched, bool ALIGN_EPI = false, bool SP2 = false>
; __device__ __forceinline__ void gemm_phase(PG8_LAS unsigned char* lds, const Gemm g, const Sched& S, const Epi& E) {
;     ...
;             PG8_WAIT_V(8); PG8_WAIT_L(0); PG8_BAR; PG8_MMA(1, 0, At, B0); PG8_MMA(1, 1, At, B1); PG8_BAR; PG8_SCHED;
;             PG8_LDB(B0, 1, 0); PG8_LDB(B1, 1, 1); PG8_SCHED; PG8_LDA(At, 1, 0); PG8_STAGE(PG8_SA(0, 1), a2 + hstepA, voffA);
;             PG8_WAIT_V(8); PG8_WAIT_L(0); PG8_BAR; PG8_MMA(0, 0, At, B0); PG8_MMA(0, 1, At, B1); PG8_BAR; PG8_SCHED;
	s_setprio 1
	s_waitcnt lgkmcnt(0)
	v_mfma_f32_16x16x32_bf16 v[62:65], v[120:123], v[160:163], v[62:65]
	v_mfma_f32_16x16x32_bf16 v[58:61], v[136:139], v[160:163], v[58:61]
	v_mfma_f32_16x16x32_bf16 v[46:49], v[120:123], v[168:171], v[46:49]
	v_mfma_f32_16x16x32_bf16 v[42:45], v[136:139], v[168:171], v[42:45]
	v_mfma_f32_16x16x32_bf16 v[30:33], v[120:123], v[184:187], v[30:33]
	v_mfma_f32_16x16x32_bf16 v[26:29], v[136:139], v[184:187], v[26:29]
	v_mfma_f32_16x16x32_bf16 v[14:17], v[120:123], v[192:195], v[14:17]
	v_mfma_f32_16x16x32_bf16 v[10:13], v[136:139], v[192:195], v[10:13]
	v_mfma_f32_16x16x32_bf16 v[62:65], v[132:135], v[164:167], v[62:65]
	v_mfma_f32_16x16x32_bf16 v[58:61], v[140:143], v[164:167], v[58:61]
	v_mfma_f32_16x16x32_bf16 v[46:49], v[132:135], v[176:179], v[46:49]
	v_mfma_f32_16x16x32_bf16 v[42:45], v[140:143], v[176:179], v[42:45]
	v_mfma_f32_16x16x32_bf16 v[30:33], v[132:135], v[188:191], v[30:33]
	v_mfma_f32_16x16x32_bf16 v[26:29], v[140:143], v[188:191], v[26:29]
	v_mfma_f32_16x16x32_bf16 v[14:17], v[132:135], v[208:211], v[14:17]
	v_mfma_f32_16x16x32_bf16 v[10:13], v[140:143], v[208:211], v[10:13]
	v_mfma_f32_16x16x32_bf16 v[54:57], v[144:147], v[160:163], v[54:57]
	v_mfma_f32_16x16x32_bf16 v[50:53], v[152:155], v[160:163], v[50:53]
	v_mfma_f32_16x16x32_bf16 v[38:41], v[144:147], v[168:171], v[38:41]
	v_mfma_f32_16x16x32_bf16 v[34:37], v[152:155], v[168:171], v[34:37]
	v_mfma_f32_16x16x32_bf16 v[22:25], v[144:147], v[184:187], v[22:25]
	v_mfma_f32_16x16x32_bf16 v[18:21], v[152:155], v[184:187], v[18:21]
	v_mfma_f32_16x16x32_bf16 v[6:9], v[144:147], v[192:195], v[6:9]
	v_mfma_f32_16x16x32_bf16 v[2:5], v[152:155], v[192:195], v[2:5]
	v_mfma_f32_16x16x32_bf16 v[54:57], v[148:151], v[164:167], v[54:57]
	v_mfma_f32_16x16x32_bf16 v[50:53], v[156:159], v[164:167], v[50:53]
	v_mfma_f32_16x16x32_bf16 v[38:41], v[148:151], v[176:179], v[38:41]
	v_mfma_f32_16x16x32_bf16 v[34:37], v[156:159], v[176:179], v[34:37]
	v_mfma_f32_16x16x32_bf16 v[22:25], v[148:151], v[188:191], v[22:25]
	v_mfma_f32_16x16x32_bf16 v[18:21], v[156:159], v[188:191], v[18:21]
	v_mfma_f32_16x16x32_bf16 v[6:9], v[148:151], v[208:211], v[6:9]
	v_mfma_f32_16x16x32_bf16 v[2:5], v[156:159], v[208:211], v[2:5]
	s_setprio 0
	s_barrier
	s_add_i32 s67, 0, 0x18000
	s_add_i32 s68, 0, 0x1c000
	v_add_u32_e32 v140, s67, v243
	v_add_u32_e32 v156, s68, v243
	ds_read_b128 v[120:123], v140
	ds_read_b128 v[132:135], v140 offset:1024
	ds_read_b128 v[136:139], v140 offset:2048
	ds_read_b128 v[140:143], v140 offset:3072
	ds_read_b128 v[144:147], v156
	ds_read_b128 v[148:151], v156 offset:1024
	ds_read_b128 v[152:155], v156 offset:2048
	ds_read_b128 v[156:159], v156 offset:3072
	s_add_u32 s48, s48, s0
	s_addc_u32 s49, s49, 0
	s_mov_b32 m0, s57
	v_lshl_add_u64 v[224:225], s[48:49], 0, v[202:203]
	ds_read_b128 v[160:163], v247 offset:32768
	ds_read_b128 v[164:167], v247 offset:33792
	ds_read_b128 v[168:171], v247 offset:34816
	ds_read_b128 v[176:179], v247 offset:35840
	ds_read_b128 v[184:187], v247 offset:36864
	ds_read_b128 v[188:191], v247 offset:37888
	ds_read_b128 v[192:195], v247 offset:38912
	ds_read_b128 v[208:211], v247 offset:39936
	global_load_lds_dwordx4 v[224:225], off
	v_lshl_add_u64 v[224:225], s[48:49], 0, v[198:199]
	s_mov_b32 m0, s58
	s_nop 0
	global_load_lds_dwordx4 v[224:225], off
	s_waitcnt vmcnt(8)
	s_waitcnt lgkmcnt(0)
	s_barrier
	s_setprio 1
	s_waitcnt lgkmcnt(0)
	v_mfma_f32_16x16x32_bf16 v[180:183], v[120:123], v[160:163], v[180:183]
	v_mfma_f32_16x16x32_bf16 v[172:175], v[136:139], v[160:163], v[172:175]
	v_mfma_f32_16x16x32_bf16 v[116:119], v[120:123], v[168:171], v[116:119]
	v_mfma_f32_16x16x32_bf16 v[112:115], v[136:139], v[168:171], v[112:115]
	v_mfma_f32_16x16x32_bf16 v[100:103], v[120:123], v[184:187], v[100:103]
	v_mfma_f32_16x16x32_bf16 v[96:99], v[136:139], v[184:187], v[96:99]
	v_mfma_f32_16x16x32_bf16 v[84:87], v[120:123], v[192:195], v[84:87]
	v_mfma_f32_16x16x32_bf16 v[74:77], v[136:139], v[192:195], v[74:77]
	v_mfma_f32_16x16x32_bf16 v[180:183], v[132:135], v[164:167], v[180:183]
	v_mfma_f32_16x16x32_bf16 v[172:175], v[140:143], v[164:167], v[172:175]
	v_mfma_f32_16x16x32_bf16 v[116:119], v[132:135], v[176:179], v[116:119]
	v_mfma_f32_16x16x32_bf16 v[112:115], v[140:143], v[176:179], v[112:115]
	v_mfma_f32_16x16x32_bf16 v[100:103], v[132:135], v[188:191], v[100:103]
	v_mfma_f32_16x16x32_bf16 v[96:99], v[140:143], v[188:191], v[96:99]
	v_mfma_f32_16x16x32_bf16 v[84:87], v[132:135], v[208:211], v[84:87]
	v_mfma_f32_16x16x32_bf16 v[74:77], v[140:143], v[208:211], v[74:77]
	v_mfma_f32_16x16x32_bf16 v[128:131], v[144:147], v[160:163], v[128:131]
	v_mfma_f32_16x16x32_bf16 v[124:127], v[152:155], v[160:163], v[124:127]
	v_mfma_f32_16x16x32_bf16 v[108:111], v[144:147], v[168:171], v[108:111]
	v_mfma_f32_16x16x32_bf16 v[104:107], v[152:155], v[168:171], v[104:107]
	v_mfma_f32_16x16x32_bf16 v[92:95], v[144:147], v[184:187], v[92:95]
	v_mfma_f32_16x16x32_bf16 v[88:91], v[152:155], v[184:187], v[88:91]
	v_mfma_f32_16x16x32_bf16 v[70:73], v[144:147], v[192:195], v[70:73]
	v_mfma_f32_16x16x32_bf16 v[66:69], v[152:155], v[192:195], v[66:69]
	v_mfma_f32_16x16x32_bf16 v[128:131], v[148:151], v[164:167], v[128:131]
	v_mfma_f32_16x16x32_bf16 v[124:127], v[156:159], v[164:167], v[124:127]
	v_mfma_f32_16x16x32_bf16 v[108:111], v[148:151], v[176:179], v[108:111]
	v_mfma_f32_16x16x32_bf16 v[104:107], v[156:159], v[176:179], v[104:107]
	v_mfma_f32_16x16x32_bf16 v[92:95], v[148:151], v[188:191], v[92:95]
	v_mfma_f32_16x16x32_bf16 v[88:91], v[156:159], v[188:191], v[88:91]
	v_mfma_f32_16x16x32_bf16 v[70:73], v[148:151], v[208:211], v[70:73]
	v_mfma_f32_16x16x32_bf16 v[66:69], v[156:159], v[208:211], v[66:69]
	s_setprio 0
	s_barrier
; #define PG8_STAGE(bufoff, gbase, voff) do { _Pragma("unroll") for (int _i = 0; _i < 2; ++_i) \
;         __builtin_amdgcn_global_load_lds((const unsigned*)((const char*)(gbase) + (voff)[_i]), (PG8_LAS unsigned*)(lds + (bufoff) + ldsw + _i * 8192), 16, 0, 0); } while (0)
; #define PG8_LDA(dst, b, h) do { _Pragma("unroll") for (int m = 0; m < 4; ++m) _Pragma("unroll") for (int k = 0; k < 2; ++k) dst[m][k] = *(const PG8_LAS bf16x8*)(lds + PG8_SA(b, h) + aoff + m * 2048 + k * 1024); } while (0)
; #define PG8_LDB(dst, b, h) do { _Pragma("unroll") for (int n = 0; n < 2; ++n) _Pragma("unroll") for (int k = 0; k < 2; ++k) dst[n][k] = *(const PG8_LAS bf16x8*)(lds + PG8_SB(b, h) + boff + n * 2048 + k * 1024); } while (0)
; template <class Epi, class Sched, bool ALIGN_EPI = false, bool SP2 = false>
; __device__ __forceinline__ void gemm_phase(PG8_LAS unsigned char* lds, const Gemm g, const Sched& S, const Epi& E) {
;     ...
;         for (int t = 0; t < nt; t += 2) {
;             const bool last = (t == nt - 2);
;             const char* a1 = cA + (size_t)(t + 1) * kstep;
;             const char* a2 = last ? nA : cA + (size_t)(t + 2) * kstep; const char* b2 = last ? nB : cB + (size_t)(t + 2) * kstep;
;             const char* a3 = a2 + kstep; const char* b3 = b2 + kstep;
;             if (last && has_next) S.a_ready(nxt);
;             if constexpr (SP2) {
;             PG8_LDB(B0, 0, 0); PG8_LDB(B1, 0, 1); PG8_SCHED; PG8_LDA(At, 0, 0); PG8_STAGE(PG8_SA(1, 1), a1 + hstepA, voffA);
;             PG8_WAIT_V(8); PG8_WAIT_L(0); PG8_BAR; PG8_MMA(0, 0, At, B0); PG8_MMA(0, 1, At, B1); PG8_BAR; PG8_SCHED;
;             PG8_LDA(At, 0, 1); PG8_STAGE(PG8_SB(0, 0), b2, voffB); PG8_STAGE(PG8_SB(0, 1), b2 + hstep, voffB); PG8_STAGE(PG8_SA(0, 0), a2, voffA);
;             PG8_WAIT_V(8); PG8_WAIT_L(0); PG8_BAR; PG8_MMA(1, 0, At, B0); PG8_MMA(1, 1, At, B1); PG8_BAR; PG8_SCHED;
;             PG8_LDB(B0, 1, 0); PG8_LDB(B1, 1, 1); PG8_SCHED; PG8_LDA(At, 1, 0); PG8_STAGE(PG8_SA(0, 1), a2 + hstepA, voffA);
;             PG8_WAIT_V(8); PG8_WAIT_L(0); PG8_BAR; PG8_MMA(0, 0, At, B0); PG8_MMA(0, 1, At, B1); PG8_BAR; PG8_SCHED;
;             PG8_LDA(At, 1, 1); PG8_STAGE(PG8_SB(1, 0), b3, voffB); PG8_STAGE(PG8_SB(1, 1), b3 + hstep, voffB); PG8_STAGE(PG8_SA(1, 0), a3, voffA);
;             PG8_WAIT_V(8); PG8_WAIT_L(0); PG8_BAR; PG8_MMA(1, 0, At, B0); PG8_MMA(1, 1, At, B1); PG8_BAR; PG8_SCHED;
	s_add_i32 s48, s67, s54
	v_lshl_add_u64 v[212:213], v[212:213], 0, s[26:27]
	s_mov_b32 m0, s48
	ds_read_b128 v[160:163], v247 offset:49152
	ds_read_b128 v[164:167], v247 offset:50176
	ds_read_b128 v[168:171], v247 offset:51200
	ds_read_b128 v[176:179], v247 offset:52224
	ds_read_b128 v[184:187], v247 offset:53248
	ds_read_b128 v[188:191], v247 offset:54272
	ds_read_b128 v[192:195], v247 offset:55296
	ds_read_b128 v[208:211], v247 offset:56320
	global_load_lds_dwordx4 v[212:213], off
	v_lshl_add_u64 v[212:213], v[214:215], 0, s[26:27]
	s_add_i32 m0, s48, 0x2000
	s_add_i32 s48, s68, s54
	global_load_lds_dwordx4 v[212:213], off
	v_lshl_add_u64 v[212:213], v[216:217], 0, s[26:27]
	s_mov_b32 m0, s48
	s_nop 0
	global_load_lds_dwordx4 v[212:213], off
	v_lshl_add_u64 v[212:213], v[218:219], 0, s[26:27]
	s_add_i32 m0, s48, 0x2000
	s_nop 0
	global_load_lds_dwordx4 v[212:213], off
	v_lshl_add_u64 v[212:213], v[220:221], 0, s[26:27]
	s_mov_b32 m0, s59
	s_nop 0
	global_load_lds_dwordx4 v[212:213], off
	v_lshl_add_u64 v[212:213], v[222:223], 0, s[26:27]
	s_mov_b32 m0, s60
	s_nop 0
	global_load_lds_dwordx4 v[212:213], off
	s_waitcnt vmcnt(8)
	s_waitcnt lgkmcnt(0)
	s_barrier
	s_setprio 1
	s_waitcnt lgkmcnt(0)
	v_mfma_f32_16x16x32_bf16 v[62:65], v[120:123], v[160:163], v[62:65]
	v_mfma_f32_16x16x32_bf16 v[58:61], v[136:139], v[160:163], v[58:61]
	v_mfma_f32_16x16x32_bf16 v[46:49], v[120:123], v[168:171], v[46:49]
	v_mfma_f32_16x16x32_bf16 v[42:45], v[136:139], v[168:171], v[42:45]
	v_mfma_f32_16x16x32_bf16 v[30:33], v[120:123], v[184:187], v[30:33]
	v_mfma_f32_16x16x32_bf16 v[26:29], v[136:139], v[184:187], v[26:29]
	v_mfma_f32_16x16x32_bf16 v[14:17], v[120:123], v[192:195], v[14:17]
	v_mfma_f32_16x16x32_bf16 v[10:13], v[136:139], v[192:195], v[10:13]
	v_mfma_f32_16x16x32_bf16 v[62:65], v[132:135], v[164:167], v[62:65]
	v_mfma_f32_16x16x32_bf16 v[58:61], v[140:143], v[164:167], v[58:61]
	v_mfma_f32_16x16x32_bf16 v[46:49], v[132:135], v[176:179], v[46:49]
	v_mfma_f32_16x16x32_bf16 v[42:45], v[140:143], v[176:179], v[42:45]
	v_mfma_f32_16x16x32_bf16 v[30:33], v[132:135], v[188:191], v[30:33]
	v_mfma_f32_16x16x32_bf16 v[26:29], v[140:143], v[188:191], v[26:29]
	v_mfma_f32_16x16x32_bf16 v[14:17], v[132:135], v[208:211], v[14:17]
	v_mfma_f32_16x16x32_bf16 v[10:13], v[140:143], v[208:211], v[10:13]
	v_mfma_f32_16x16x32_bf16 v[54:57], v[144:147], v[160:163], v[54:57]
	v_mfma_f32_16x16x32_bf16 v[50:53], v[152:155], v[160:163], v[50:53]
	v_mfma_f32_16x16x32_bf16 v[38:41], v[144:147], v[168:171], v[38:41]
	v_mfma_f32_16x16x32_bf16 v[34:37], v[152:155], v[168:171], v[34:37]
	v_mfma_f32_16x16x32_bf16 v[22:25], v[144:147], v[184:187], v[22:25]
	v_mfma_f32_16x16x32_bf16 v[18:21], v[152:155], v[184:187], v[18:21]
	v_mfma_f32_16x16x32_bf16 v[6:9], v[144:147], v[192:195], v[6:9]
	v_mfma_f32_16x16x32_bf16 v[2:5], v[152:155], v[192:195], v[2:5]
	v_mfma_f32_16x16x32_bf16 v[54:57], v[148:151], v[164:167], v[54:57]
	v_mfma_f32_16x16x32_bf16 v[50:53], v[156:159], v[164:167], v[50:53]
	v_mfma_f32_16x16x32_bf16 v[38:41], v[148:151], v[176:179], v[38:41]
	v_mfma_f32_16x16x32_bf16 v[34:37], v[156:159], v[176:179], v[34:37]
	v_mfma_f32_16x16x32_bf16 v[22:25], v[148:151], v[188:191], v[22:25]
	v_mfma_f32_16x16x32_bf16 v[18:21], v[156:159], v[188:191], v[18:21]
	v_mfma_f32_16x16x32_bf16 v[6:9], v[148:151], v[208:211], v[6:9]
	v_mfma_f32_16x16x32_bf16 v[2:5], v[156:159], v[208:211], v[2:5]
	s_setprio 0
	s_barrier
	s_add_u32 s46, s46, 0x100
	s_addc_u32 s47, s47, 0
	s_add_u32 s5, s5, 0x100
	s_addc_u32 s19, s19, 0
	s_cmp_ge_u32 s66, s61
	s_mov_b32 s48, s66
	s_cbranch_scc0 .LBB0_600
	s_and_b64 vcc, exec, s[10:11]
	s_cbranch_vccz .LBB0_603
	s_barrier

; #define PG8_STAGE(bufoff, gbase, voff) do { _Pragma("unroll") for (int _i = 0; _i < 2; ++_i) \
;         __builtin_amdgcn_global_load_lds((const unsigned*)((const char*)(gbase) + (voff)[_i]), (PG8_LAS unsigned*)(lds + (bufoff) + ldsw + _i * 8192), 16, 0, 0); } while (0)
; #define PG8_LDA(dst, b, h) do { _Pragma("unroll") for (int m = 0; m < 4; ++m) _Pragma("unroll") for (int k = 0; k < 2; ++k) dst[m][k] = *(const PG8_LAS bf16x8*)(lds + PG8_SA(b, h) + aoff + m * 2048 + k * 1024); } while (0)
; #define PG8_LDB(dst, b, h) do { _Pragma("unroll") for (int n = 0; n < 2; ++n) _Pragma("unroll") for (int k = 0; k < 2; ++k) dst[n][k] = *(const PG8_LAS bf16x8*)(lds + PG8_SB(b, h) + boff + n * 2048 + k * 1024); } while (0)
; #define PG8_MMA(ai, bj, At, Bt) do { __builtin_amdgcn_s_setprio(1); _Pragma("unroll") for (int m = 0; m < 4; ++m) _Pragma("unroll") for (int n = 0; n < 2; ++n) _Pragma("unroll") for (int k = 0; k < 2; ++k) \
;         acc[ai][bj][m][n] = __builtin_amdgcn_mfma_f32_16x16x32_bf16(Bt[n][k], At[m][k], acc[ai][bj][m][n], 0, 0, 0); __builtin_amdgcn_s_setprio(0); } while (0)
; #define PG8_WAIT_V(n) asm volatile("s_waitcnt vmcnt(" #n ")" ::: "memory")
; #define PG8_WAIT_L(n) asm volatile("s_waitcnt lgkmcnt(" #n ")" ::: "memory")
; template <class Epi, class Sched, bool ALIGN_EPI = false, bool SP2 = false>
; __device__ __forceinline__ void gemm_phase(PG8_LAS unsigned char* lds, const Gemm g, const Sched& S, const Epi& E) {
;     ...
;             const bool last = (t == nt - 2);
;             const char* a1 = cA + (size_t)(t + 1) * kstep;
;             const char* a2 = last ? nA : cA + (size_t)(t + 2) * kstep; const char* b2 = last ? nB : cB + (size_t)(t + 2) * kstep;
;             const char* a3 = a2 + kstep; const char* b3 = b2 + kstep;
;             if (last && has_next) S.a_ready(nxt);
;             if constexpr (SP2) {
;             PG8_LDB(B0, 0, 0); PG8_LDB(B1, 0, 1); PG8_SCHED; PG8_LDA(At, 0, 0); PG8_STAGE(PG8_SA(1, 1), a1 + hstepA, voffA);
;             PG8_WAIT_V(8); PG8_WAIT_L(0); PG8_BAR; PG8_MMA(0, 0, At, B0); PG8_MMA(0, 1, At, B1); PG8_BAR; PG8_SCHED;
;             PG8_LDA(At, 0, 1); PG8_STAGE(PG8_SB(0, 0), b2, voffB); PG8_STAGE(PG8_SB(0, 1), b2 + hstep, voffB); PG8_STAGE(PG8_SA(0, 0), a2, voffA);
;             PG8_WAIT_V(8); PG8_WAIT_L(0); PG8_BAR; PG8_MMA(1, 0, At, B0); PG8_MMA(1, 1, At, B1); PG8_BAR; PG8_SCHED;
.LBB0_636:
	s_add_u32 s44, s42, 0xfffc0080
	s_addc_u32 s45, s43, -1
	s_add_i32 s60, 0, 0x10000
	s_cmp_eq_u32 s59, 12
	s_cselect_b32 s47, s19, s45
	s_cselect_b32 s46, s55, s44
	v_add_u32_e32 v150, s60, v151
	s_cselect_b32 s45, s11, s58
	s_cselect_b32 s44, s56, s57
	s_add_i32 s62, 0, 0x14000
	ds_read_b128 v[146:149], v150
	ds_read_b128 v[152:155], v150 offset:1024
	ds_read_b128 v[162:165], v150 offset:2048
	ds_read_b128 v[166:169], v150 offset:3072
	v_add_u32_e32 v150, s62, v151
	ds_read_b128 v[170:173], v150
	ds_read_b128 v[174:177], v150 offset:1024
	ds_read_b128 v[178:181], v150 offset:2048
	ds_read_b128 v[182:185], v150 offset:3072
	v_lshl_add_u64 v[158:159], s[42:43], 0, v[142:143]
	s_add_i32 m0, s16, 0xc000
	ds_read_b128 v[186:189], v161
	ds_read_b128 v[190:193], v161 offset:1024
	ds_read_b128 v[198:201], v161 offset:2048
	ds_read_b128 v[202:205], v161 offset:3072
	ds_read_b128 v[206:209], v161 offset:4096
	ds_read_b128 v[210:213], v161 offset:5120
	ds_read_b128 v[214:217], v161 offset:6144
	ds_read_b128 v[218:221], v161 offset:7168
	global_load_lds_dwordx4 v[158:159], off
	v_lshl_add_u64 v[158:159], s[42:43], 0, v[144:145]
	s_add_i32 m0, s16, 0xe000
	s_nop 0
	global_load_lds_dwordx4 v[158:159], off
	s_waitcnt vmcnt(8)
	s_waitcnt lgkmcnt(0)
	s_barrier
	s_setprio 1
	s_waitcnt lgkmcnt(0)
	v_mfma_f32_16x16x32_bf16 v[132:135], v[146:149], v[186:189], v[132:135]
	v_mfma_f32_16x16x32_bf16 v[128:131], v[162:165], v[186:189], v[128:131]
	v_mfma_f32_16x16x32_bf16 v[116:119], v[146:149], v[198:201], v[116:119]
	v_mfma_f32_16x16x32_bf16 v[112:115], v[162:165], v[198:201], v[112:115]
	v_mfma_f32_16x16x32_bf16 v[100:103], v[146:149], v[206:209], v[100:103]
	v_mfma_f32_16x16x32_bf16 v[96:99], v[162:165], v[206:209], v[96:99]
	v_mfma_f32_16x16x32_bf16 v[84:87], v[146:149], v[214:217], v[84:87]
	v_mfma_f32_16x16x32_bf16 v[74:77], v[162:165], v[214:217], v[74:77]
	v_mfma_f32_16x16x32_bf16 v[132:135], v[152:155], v[190:193], v[132:135]
	v_mfma_f32_16x16x32_bf16 v[128:131], v[166:169], v[190:193], v[128:131]
	v_mfma_f32_16x16x32_bf16 v[116:119], v[152:155], v[202:205], v[116:119]
	v_mfma_f32_16x16x32_bf16 v[112:115], v[166:169], v[202:205], v[112:115]
	v_mfma_f32_16x16x32_bf16 v[100:103], v[152:155], v[210:213], v[100:103]
	v_mfma_f32_16x16x32_bf16 v[96:99], v[166:169], v[210:213], v[96:99]
	v_mfma_f32_16x16x32_bf16 v[84:87], v[152:155], v[218:221], v[84:87]
	v_mfma_f32_16x16x32_bf16 v[74:77], v[166:169], v[218:221], v[74:77]
	v_mfma_f32_16x16x32_bf16 v[124:127], v[170:173], v[186:189], v[124:127]
	v_mfma_f32_16x16x32_bf16 v[120:123], v[178:181], v[186:189], v[120:123]
	v_mfma_f32_16x16x32_bf16 v[108:111], v[170:173], v[198:201], v[108:111]
	v_mfma_f32_16x16x32_bf16 v[104:107], v[178:181], v[198:201], v[104:107]
	v_mfma_f32_16x16x32_bf16 v[92:95], v[170:173], v[206:209], v[92:95]
	v_mfma_f32_16x16x32_bf16 v[88:91], v[178:181], v[206:209], v[88:91]
	v_mfma_f32_16x16x32_bf16 v[70:73], v[170:173], v[214:217], v[70:73]
	v_mfma_f32_16x16x32_bf16 v[66:69], v[178:181], v[214:217], v[66:69]
	v_mfma_f32_16x16x32_bf16 v[124:127], v[174:177], v[190:193], v[124:127]
	v_mfma_f32_16x16x32_bf16 v[120:123], v[182:185], v[190:193], v[120:123]
	v_mfma_f32_16x16x32_bf16 v[108:111], v[174:177], v[202:205], v[108:111]
	v_mfma_f32_16x16x32_bf16 v[104:107], v[182:185], v[202:205], v[104:107]
	v_mfma_f32_16x16x32_bf16 v[92:95], v[174:177], v[210:213], v[92:95]
	v_mfma_f32_16x16x32_bf16 v[88:91], v[182:185], v[210:213], v[88:91]
	v_mfma_f32_16x16x32_bf16 v[70:73], v[174:177], v[218:221], v[70:73]
	v_mfma_f32_16x16x32_bf16 v[66:69], v[182:185], v[218:221], v[66:69]
	s_setprio 0
	s_barrier
	s_add_i32 s60, s60, s0
	v_lshl_add_u64 v[158:159], s[44:45], 0, v[138:139]
	s_mov_b32 m0, s60
	ds_read_b128 v[186:189], v161 offset:16384
	ds_read_b128 v[190:193], v161 offset:17408
	ds_read_b128 v[198:201], v161 offset:18432
	ds_read_b128 v[202:205], v161 offset:19456
	ds_read_b128 v[206:209], v161 offset:20480
	ds_read_b128 v[210:213], v161 offset:21504
	ds_read_b128 v[214:217], v161 offset:22528
	ds_read_b128 v[218:221], v161 offset:23552
	global_load_lds_dwordx4 v[158:159], off
	s_add_i32 m0, s60, 0x2000
	s_add_u32 s60, s44, 0x40000
	v_lshl_add_u64 v[194:195], s[44:45], 0, v[78:79]
	s_addc_u32 s61, s45, 0
	s_add_i32 s62, s62, s0
	global_load_lds_dwordx4 v[194:195], off
	v_lshl_add_u64 v[222:223], s[60:61], 0, v[138:139]
	s_mov_b32 m0, s62
	v_lshl_add_u64 v[224:225], s[46:47], 0, v[136:137]
	global_load_lds_dwordx4 v[222:223], off
	v_lshl_add_u64 v[222:223], s[60:61], 0, v[78:79]
	s_add_i32 m0, s62, 0x2000
	s_nop 0
	global_load_lds_dwordx4 v[222:223], off
	v_lshl_add_u64 v[222:223], s[46:47], 0, v[140:141]
	s_mov_b32 m0, s16
	s_nop 0
	global_load_lds_dwordx4 v[222:223], off
	s_mov_b32 m0, s17
	s_nop 0
	global_load_lds_dwordx4 v[224:225], off
	s_waitcnt vmcnt(8)
	s_waitcnt lgkmcnt(0)
	s_barrier
; #define PG8_STAGE(bufoff, gbase, voff) do { _Pragma("unroll") for (int _i = 0; _i < 2; ++_i) \
;         __builtin_amdgcn_global_load_lds((const unsigned*)((const char*)(gbase) + (voff)[_i]), (PG8_LAS unsigned*)(lds + (bufoff) + ldsw + _i * 8192), 16, 0, 0); } while (0)
; #define PG8_LDA(dst, b, h) do { _Pragma("unroll") for (int m = 0; m < 4; ++m) _Pragma("unroll") for (int k = 0; k < 2; ++k) dst[m][k] = *(const PG8_LAS bf16x8*)(lds + PG8_SA(b, h) + aoff + m * 2048 + k * 1024); } while (0)
; #define PG8_LDB(dst, b, h) do { _Pragma("unroll") for (int n = 0; n < 2; ++n) _Pragma("unroll") for (int k = 0; k < 2; ++k) dst[n][k] = *(const PG8_LAS bf16x8*)(lds + PG8_SB(b, h) + boff + n * 2048 + k * 1024); } while (0)
; #define PG8_MMA(ai, bj, At, Bt) do { __builtin_amdgcn_s_setprio(1); _Pragma("unroll") for (int m = 0; m < 4; ++m) _Pragma("unroll") for (int n = 0; n < 2; ++n) _Pragma("unroll") for (int k = 0; k < 2; ++k) \
;         acc[ai][bj][m][n] = __builtin_amdgcn_mfma_f32_16x16x32_bf16(Bt[n][k], At[m][k], acc[ai][bj][m][n], 0, 0, 0); __builtin_amdgcn_s_setprio(0); } while (0)
; #define PG8_WAIT_V(n) asm volatile("s_waitcnt vmcnt(" #n ")" ::: "memory")
; #define PG8_WAIT_L(n) asm volatile("s_waitcnt lgkmcnt(" #n ")" ::: "memory")
; #define PG8_BAR __builtin_amdgcn_s_barrier()
; #define PG8_SCHED __builtin_amdgcn_sched_barrier(0)
; template <class Epi, class Sched, bool ALIGN_EPI = false, bool SP2 = false>
; __device__ __forceinline__ void gemm_phase(PG8_LAS unsigned char* lds, const Gemm g, const Sched& S, const Epi& E) {
;     ...
;             PG8_WAIT_V(8); PG8_WAIT_L(0); PG8_BAR; PG8_MMA(1, 0, At, B0); PG8_MMA(1, 1, At, B1); PG8_BAR; PG8_SCHED;
;             PG8_LDB(B0, 1, 0); PG8_LDB(B1, 1, 1); PG8_SCHED; PG8_LDA(At, 1, 0); PG8_STAGE(PG8_SA(0, 1), a2 + hstepA, voffA);
;             PG8_WAIT_V(8); PG8_WAIT_L(0); PG8_BAR; PG8_MMA(0, 0, At, B0); PG8_MMA(0, 1, At, B1); PG8_BAR; PG8_SCHED;
	s_setprio 1
	s_waitcnt lgkmcnt(0)
	v_mfma_f32_16x16x32_bf16 v[62:65], v[146:149], v[186:189], v[62:65]
	v_mfma_f32_16x16x32_bf16 v[58:61], v[162:165], v[186:189], v[58:61]
	v_mfma_f32_16x16x32_bf16 v[46:49], v[146:149], v[198:201], v[46:49]
	v_mfma_f32_16x16x32_bf16 v[42:45], v[162:165], v[198:201], v[42:45]
	v_mfma_f32_16x16x32_bf16 v[30:33], v[146:149], v[206:209], v[30:33]
	v_mfma_f32_16x16x32_bf16 v[26:29], v[162:165], v[206:209], v[26:29]
	v_mfma_f32_16x16x32_bf16 v[14:17], v[146:149], v[214:217], v[14:17]
	v_mfma_f32_16x16x32_bf16 v[10:13], v[162:165], v[214:217], v[10:13]
	v_mfma_f32_16x16x32_bf16 v[62:65], v[152:155], v[190:193], v[62:65]
	v_mfma_f32_16x16x32_bf16 v[58:61], v[166:169], v[190:193], v[58:61]
	v_mfma_f32_16x16x32_bf16 v[46:49], v[152:155], v[202:205], v[46:49]
	v_mfma_f32_16x16x32_bf16 v[42:45], v[166:169], v[202:205], v[42:45]
	v_mfma_f32_16x16x32_bf16 v[30:33], v[152:155], v[210:213], v[30:33]
	v_mfma_f32_16x16x32_bf16 v[26:29], v[166:169], v[210:213], v[26:29]
	v_mfma_f32_16x16x32_bf16 v[14:17], v[152:155], v[218:221], v[14:17]
	v_mfma_f32_16x16x32_bf16 v[10:13], v[166:169], v[218:221], v[10:13]
	v_mfma_f32_16x16x32_bf16 v[54:57], v[170:173], v[186:189], v[54:57]
	v_mfma_f32_16x16x32_bf16 v[50:53], v[178:181], v[186:189], v[50:53]
	v_mfma_f32_16x16x32_bf16 v[38:41], v[170:173], v[198:201], v[38:41]
	v_mfma_f32_16x16x32_bf16 v[34:37], v[178:181], v[198:201], v[34:37]
	v_mfma_f32_16x16x32_bf16 v[22:25], v[170:173], v[206:209], v[22:25]
	v_mfma_f32_16x16x32_bf16 v[18:21], v[178:181], v[206:209], v[18:21]
	v_mfma_f32_16x16x32_bf16 v[6:9], v[170:173], v[214:217], v[6:9]
	v_mfma_f32_16x16x32_bf16 v[2:5], v[178:181], v[214:217], v[2:5]
	v_mfma_f32_16x16x32_bf16 v[54:57], v[174:177], v[190:193], v[54:57]
	v_mfma_f32_16x16x32_bf16 v[50:53], v[182:185], v[190:193], v[50:53]
	v_mfma_f32_16x16x32_bf16 v[38:41], v[174:177], v[202:205], v[38:41]
	v_mfma_f32_16x16x32_bf16 v[34:37], v[182:185], v[202:205], v[34:37]
	v_mfma_f32_16x16x32_bf16 v[22:25], v[174:177], v[210:213], v[22:25]
	v_mfma_f32_16x16x32_bf16 v[18:21], v[182:185], v[210:213], v[18:21]
	v_mfma_f32_16x16x32_bf16 v[6:9], v[174:177], v[218:221], v[6:9]
	v_mfma_f32_16x16x32_bf16 v[2:5], v[182:185], v[218:221], v[2:5]
	s_setprio 0
	s_barrier
	s_add_i32 s60, 0, 0x18000
	v_add_u32_e32 v150, s60, v151
	s_add_i32 s61, 0, 0x1c000
	ds_read_b128 v[146:149], v150
	ds_read_b128 v[152:155], v150 offset:1024
	ds_read_b128 v[162:165], v150 offset:2048
	ds_read_b128 v[166:169], v150 offset:3072
	v_add_u32_e32 v150, s61, v151
	ds_read_b128 v[170:173], v150
	ds_read_b128 v[174:177], v150 offset:1024
	ds_read_b128 v[178:181], v150 offset:2048
	ds_read_b128 v[182:185], v150 offset:3072
	s_add_u32 s46, s46, 0x40000
	s_addc_u32 s47, s47, 0
	s_mov_b32 m0, s37
	v_lshl_add_u64 v[226:227], s[46:47], 0, v[140:141]
	ds_read_b128 v[186:189], v161 offset:32768
	ds_read_b128 v[190:193], v161 offset:33792
	ds_read_b128 v[198:201], v161 offset:34816
	ds_read_b128 v[202:205], v161 offset:35840
	ds_read_b128 v[206:209], v161 offset:36864
	ds_read_b128 v[210:213], v161 offset:37888
	ds_read_b128 v[214:217], v161 offset:38912
	ds_read_b128 v[218:221], v161 offset:39936
	global_load_lds_dwordx4 v[226:227], off
	v_lshl_add_u64 v[226:227], s[46:47], 0, v[136:137]
	s_mov_b32 m0, s48
	s_nop 0
	global_load_lds_dwordx4 v[226:227], off
	s_waitcnt vmcnt(8)
	s_waitcnt lgkmcnt(0)
	s_barrier
	s_setprio 1
	s_waitcnt lgkmcnt(0)
	v_mfma_f32_16x16x32_bf16 v[132:135], v[146:149], v[186:189], v[132:135]
	v_mfma_f32_16x16x32_bf16 v[128:131], v[162:165], v[186:189], v[128:131]
	v_mfma_f32_16x16x32_bf16 v[116:119], v[146:149], v[198:201], v[116:119]
	v_mfma_f32_16x16x32_bf16 v[112:115], v[162:165], v[198:201], v[112:115]
	v_mfma_f32_16x16x32_bf16 v[100:103], v[146:149], v[206:209], v[100:103]
	v_mfma_f32_16x16x32_bf16 v[96:99], v[162:165], v[206:209], v[96:99]
	v_mfma_f32_16x16x32_bf16 v[84:87], v[146:149], v[214:217], v[84:87]
	v_mfma_f32_16x16x32_bf16 v[74:77], v[162:165], v[214:217], v[74:77]
	v_mfma_f32_16x16x32_bf16 v[132:135], v[152:155], v[190:193], v[132:135]
	v_mfma_f32_16x16x32_bf16 v[128:131], v[166:169], v[190:193], v[128:131]
	v_mfma_f32_16x16x32_bf16 v[116:119], v[152:155], v[202:205], v[116:119]
	v_mfma_f32_16x16x32_bf16 v[112:115], v[166:169], v[202:205], v[112:115]
	v_mfma_f32_16x16x32_bf16 v[100:103], v[152:155], v[210:213], v[100:103]
	v_mfma_f32_16x16x32_bf16 v[96:99], v[166:169], v[210:213], v[96:99]
	v_mfma_f32_16x16x32_bf16 v[84:87], v[152:155], v[218:221], v[84:87]
	v_mfma_f32_16x16x32_bf16 v[74:77], v[166:169], v[218:221], v[74:77]
	v_mfma_f32_16x16x32_bf16 v[124:127], v[170:173], v[186:189], v[124:127]
	v_mfma_f32_16x16x32_bf16 v[120:123], v[178:181], v[186:189], v[120:123]
	v_mfma_f32_16x16x32_bf16 v[108:111], v[170:173], v[198:201], v[108:111]
	v_mfma_f32_16x16x32_bf16 v[104:107], v[178:181], v[198:201], v[104:107]
	v_mfma_f32_16x16x32_bf16 v[92:95], v[170:173], v[206:209], v[92:95]
	v_mfma_f32_16x16x32_bf16 v[88:91], v[178:181], v[206:209], v[88:91]
	v_mfma_f32_16x16x32_bf16 v[70:73], v[170:173], v[214:217], v[70:73]
	v_mfma_f32_16x16x32_bf16 v[66:69], v[178:181], v[214:217], v[66:69]
	v_mfma_f32_16x16x32_bf16 v[124:127], v[174:177], v[190:193], v[124:127]
	v_mfma_f32_16x16x32_bf16 v[120:123], v[182:185], v[190:193], v[120:123]
	v_mfma_f32_16x16x32_bf16 v[108:111], v[174:177], v[202:205], v[108:111]
	v_mfma_f32_16x16x32_bf16 v[104:107], v[182:185], v[202:205], v[104:107]
	v_mfma_f32_16x16x32_bf16 v[92:95], v[174:177], v[210:213], v[92:95]
	v_mfma_f32_16x16x32_bf16 v[88:91], v[182:185], v[210:213], v[88:91]
	v_mfma_f32_16x16x32_bf16 v[70:73], v[174:177], v[218:221], v[70:73]
	v_mfma_f32_16x16x32_bf16 v[66:69], v[182:185], v[218:221], v[66:69]
	s_setprio 0
	s_barrier
; #define PG8_WAIT_V(n) asm volatile("s_waitcnt vmcnt(" #n ")" ::: "memory")
; #define PG8_WAIT_L(n) asm volatile("s_waitcnt lgkmcnt(" #n ")" ::: "memory")
;     __device__ __forceinline__ void operator()(const f32x4 (&acc)[2][2][4][2], const Unit& u, int wr, int wc, int fr, int fq) const {
;     ...
;         float rs8[2][4]; rstd8(ssq, row0, rs8);
; #pragma unroll
;         for (int ai = 0; ai < 2; ++ai)
; #pragma unroll
;             for (int m = 0; m < 4; ++m) { const int row = row0 + ai * HALF + m * 16; bf16_t* rowp = O + (size_t)row * ldc + col0; const float rs = rs8[ai][m];
;                 const f32x4 g0 = acc[ai][0][m][0] * rs, g1 = acc[ai][0][m][1] * rs, u0 = acc[ai][1][m][0] * rs, u1 = acc[ai][1][m][1] * rs;
; template <class Epi, class Sched, bool ALIGN_EPI = false, bool SP2 = false>
; __device__ __forceinline__ void gemm_phase(PG8_LAS unsigned char* lds, const Gemm g, const Sched& S, const Epi& E) {
;     ...
;         for (int t = 0; t < nt; t += 2) {
;             const bool last = (t == nt - 2);
;             const char* a1 = cA + (size_t)(t + 1) * kstep;
;             const char* a2 = last ? nA : cA + (size_t)(t + 2) * kstep; const char* b2 = last ? nB : cB + (size_t)(t + 2) * kstep;
;             const char* a3 = a2 + kstep; const char* b3 = b2 + kstep;
;             if (last && has_next) S.a_ready(nxt);
;             if constexpr (SP2) {
;             PG8_LDB(B0, 0, 0); PG8_LDB(B1, 0, 1); PG8_SCHED; PG8_LDA(At, 0, 0); PG8_STAGE(PG8_SA(1, 1), a1 + hstepA, voffA);
;             PG8_WAIT_V(8); PG8_WAIT_L(0); PG8_BAR; PG8_MMA(0, 0, At, B0); PG8_MMA(0, 1, At, B1); PG8_BAR; PG8_SCHED;
;             PG8_LDA(At, 0, 1); PG8_STAGE(PG8_SB(0, 0), b2, voffB); PG8_STAGE(PG8_SB(0, 1), b2 + hstep, voffB); PG8_STAGE(PG8_SA(0, 0), a2, voffA);
;             PG8_WAIT_V(8); PG8_WAIT_L(0); PG8_BAR; PG8_MMA(1, 0, At, B0); PG8_MMA(1, 1, At, B1); PG8_BAR; PG8_SCHED;
;             PG8_LDB(B0, 1, 0); PG8_LDB(B1, 1, 1); PG8_SCHED; PG8_LDA(At, 1, 0); PG8_STAGE(PG8_SA(0, 1), a2 + hstepA, voffA);
;             PG8_WAIT_V(8); PG8_WAIT_L(0); PG8_BAR; PG8_MMA(0, 0, At, B0); PG8_MMA(0, 1, At, B1); PG8_BAR; PG8_SCHED;
;             PG8_LDA(At, 1, 1); PG8_STAGE(PG8_SB(1, 0), b3, voffB); PG8_STAGE(PG8_SB(1, 1), b3 + hstep, voffB); PG8_STAGE(PG8_SA(1, 0), a3, voffA);
;             PG8_WAIT_V(8); PG8_WAIT_L(0); PG8_BAR; PG8_MMA(1, 0, At, B0); PG8_MMA(1, 1, At, B1); PG8_BAR; PG8_SCHED;
	s_add_i32 s46, s60, s0
	v_lshl_add_u64 v[158:159], v[158:159], 0, s[26:27]
	s_mov_b32 m0, s46
	ds_read_b128 v[186:189], v161 offset:49152
	ds_read_b128 v[190:193], v161 offset:50176
	ds_read_b128 v[198:201], v161 offset:51200
	ds_read_b128 v[202:205], v161 offset:52224
	ds_read_b128 v[206:209], v161 offset:53248
	ds_read_b128 v[210:213], v161 offset:54272
	ds_read_b128 v[214:217], v161 offset:55296
	ds_read_b128 v[218:221], v161 offset:56320
	global_load_lds_dwordx4 v[158:159], off
	s_add_i32 m0, s46, 0x2000
	s_add_u32 s44, s44, 0x40080
	v_lshl_add_u64 v[158:159], v[194:195], 0, s[26:27]
	s_addc_u32 s45, s45, 0
	s_add_i32 s46, s61, s0
	global_load_lds_dwordx4 v[158:159], off
	v_lshl_add_u64 v[158:159], s[44:45], 0, v[138:139]
	s_mov_b32 m0, s46
	s_nop 0
	global_load_lds_dwordx4 v[158:159], off
	v_lshl_add_u64 v[158:159], s[44:45], 0, v[78:79]
	s_add_i32 m0, s46, 0x2000
	s_nop 0
	global_load_lds_dwordx4 v[158:159], off
	v_lshl_add_u64 v[158:159], v[222:223], 0, s[26:27]
	s_mov_b32 m0, s49
	s_nop 0
	global_load_lds_dwordx4 v[158:159], off
	v_lshl_add_u64 v[158:159], v[224:225], 0, s[26:27]
	s_mov_b32 m0, s53
	s_nop 0
	global_load_lds_dwordx4 v[158:159], off
	s_waitcnt vmcnt(8)
	s_waitcnt lgkmcnt(0)
	s_barrier
	s_setprio 1
	s_waitcnt lgkmcnt(0)
	v_mfma_f32_16x16x32_bf16 v[62:65], v[146:149], v[186:189], v[62:65]
	v_mfma_f32_16x16x32_bf16 v[58:61], v[162:165], v[186:189], v[58:61]
	v_mfma_f32_16x16x32_bf16 v[46:49], v[146:149], v[198:201], v[46:49]
	v_mfma_f32_16x16x32_bf16 v[42:45], v[162:165], v[198:201], v[42:45]
	v_mfma_f32_16x16x32_bf16 v[30:33], v[146:149], v[206:209], v[30:33]
	v_mfma_f32_16x16x32_bf16 v[26:29], v[162:165], v[206:209], v[26:29]
	v_mfma_f32_16x16x32_bf16 v[14:17], v[146:149], v[214:217], v[14:17]
	v_mfma_f32_16x16x32_bf16 v[10:13], v[162:165], v[214:217], v[10:13]
	v_mfma_f32_16x16x32_bf16 v[62:65], v[152:155], v[190:193], v[62:65]
	v_mfma_f32_16x16x32_bf16 v[58:61], v[166:169], v[190:193], v[58:61]
	v_mfma_f32_16x16x32_bf16 v[46:49], v[152:155], v[202:205], v[46:49]
	v_mfma_f32_16x16x32_bf16 v[42:45], v[166:169], v[202:205], v[42:45]
	v_mfma_f32_16x16x32_bf16 v[30:33], v[152:155], v[210:213], v[30:33]
	v_mfma_f32_16x16x32_bf16 v[26:29], v[166:169], v[210:213], v[26:29]
	v_mfma_f32_16x16x32_bf16 v[14:17], v[152:155], v[218:221], v[14:17]
	v_mfma_f32_16x16x32_bf16 v[10:13], v[166:169], v[218:221], v[10:13]
	v_mfma_f32_16x16x32_bf16 v[54:57], v[170:173], v[186:189], v[54:57]
	v_mfma_f32_16x16x32_bf16 v[50:53], v[178:181], v[186:189], v[50:53]
	v_mfma_f32_16x16x32_bf16 v[38:41], v[170:173], v[198:201], v[38:41]
	v_mfma_f32_16x16x32_bf16 v[34:37], v[178:181], v[198:201], v[34:37]
	v_mfma_f32_16x16x32_bf16 v[22:25], v[170:173], v[206:209], v[22:25]
	v_mfma_f32_16x16x32_bf16 v[18:21], v[178:181], v[206:209], v[18:21]
	v_mfma_f32_16x16x32_bf16 v[6:9], v[170:173], v[214:217], v[6:9]
	v_mfma_f32_16x16x32_bf16 v[2:5], v[178:181], v[214:217], v[2:5]
	v_mfma_f32_16x16x32_bf16 v[54:57], v[174:177], v[190:193], v[54:57]
	v_mfma_f32_16x16x32_bf16 v[50:53], v[182:185], v[190:193], v[50:53]
	v_mfma_f32_16x16x32_bf16 v[38:41], v[174:177], v[202:205], v[38:41]
	v_mfma_f32_16x16x32_bf16 v[34:37], v[182:185], v[202:205], v[34:37]
	v_mfma_f32_16x16x32_bf16 v[22:25], v[174:177], v[210:213], v[22:25]
	v_mfma_f32_16x16x32_bf16 v[18:21], v[182:185], v[210:213], v[18:21]
	v_mfma_f32_16x16x32_bf16 v[6:9], v[174:177], v[218:221], v[6:9]
	v_mfma_f32_16x16x32_bf16 v[2:5], v[182:185], v[218:221], v[2:5]
	s_setprio 0
	s_barrier
	s_add_i32 s59, s59, 2
	s_add_u32 s42, s42, 0x100
	s_addc_u32 s43, s43, 0
	s_add_u32 s57, s57, 0x100
	s_addc_u32 s58, s58, 0
	s_cmp_gt_u32 s59, 13
	s_cbranch_scc0 .LBB0_636
	v_lshl_add_u32 v154, s5, 8, v1
	v_ashrrev_i32_e32 v155, 31, v154
	v_lshl_add_u64 v[146:147], v[154:155], 4, s[28:29]
	v_or_b32_e32 v174, 16, v154
	global_load_dwordx4 v[180:183], v[146:147], off
	v_ashrrev_i32_e32 v175, 31, v174
	v_lshl_add_u64 v[146:147], v[174:175], 4, s[28:29]
	v_or_b32_e32 v170, 32, v154
	global_load_dwordx4 v[184:187], v[146:147], off
	v_ashrrev_i32_e32 v171, 31, v170
	v_lshl_add_u64 v[146:147], v[170:171], 4, s[28:29]
	v_or_b32_e32 v166, 48, v154
	global_load_dwordx4 v[188:191], v[146:147], off
	v_ashrrev_i32_e32 v167, 31, v166
	v_lshl_add_u64 v[146:147], v[166:167], 4, s[28:29]
	v_add_u32_e32 v162, 0x80, v154
	global_load_dwordx4 v[192:195], v[146:147], off
	v_ashrrev_i32_e32 v163, 31, v162
	v_lshl_add_u64 v[146:147], v[162:163], 4, s[28:29]
	v_add_u32_e32 v158, 0x90, v154
	global_load_dwordx4 v[198:201], v[146:147], off
	v_ashrrev_i32_e32 v159, 31, v158
	v_add_u32_e32 v148, 0xa0, v154
	v_lshl_add_u64 v[146:147], v[158:159], 4, s[28:29]
	v_ashrrev_i32_e32 v149, 31, v148
	global_load_dwordx4 v[202:205], v[146:147], off
	v_lshl_add_u64 v[146:147], v[148:149], 4, s[28:29]
	global_load_dwordx4 v[206:209], v[146:147], off
	v_add_u32_e32 v146, 0xb0, v154
	v_ashrrev_i32_e32 v147, 31, v146
	v_lshl_add_u64 v[152:153], v[146:147], 4, s[28:29]
	global_load_dwordx4 v[210:213], v[152:153], off
	v_mul_f32_e32 v124, v132, v124
	v_mul_f32_e32 v125, v133, v125
	v_mul_f32_e32 v126, v134, v126
	v_mul_f32_e32 v127, v135, v127
	v_mul_f32_e32 v120, v128, v120
	v_mul_f32_e32 v121, v129, v121
	v_mul_f32_e32 v122, v130, v122
	v_mul_f32_e32 v123, v131, v123
	v_mul_f32_e32 v108, v116, v108
	v_mul_f32_e32 v109, v117, v109
	v_mul_f32_e32 v110, v118, v110
	v_mul_f32_e32 v111, v119, v111
	v_mul_f32_e32 v104, v112, v104
	v_mul_f32_e32 v105, v113, v105
	v_mul_f32_e32 v106, v114, v106
	v_mul_f32_e32 v107, v115, v107
	v_mul_f32_e32 v92, v100, v92
	v_mul_f32_e32 v93, v101, v93
	v_mul_f32_e32 v94, v102, v94
	v_mul_f32_e32 v95, v103, v95
	v_mul_f32_e32 v88, v96, v88
	v_mul_f32_e32 v89, v97, v89
	v_mul_f32_e32 v90, v98, v90
	v_mul_f32_e32 v91, v99, v91
	v_mul_f32_e32 v70, v84, v70
	v_mul_f32_e32 v71, v85, v71
	v_mul_f32_e32 v72, v86, v72
	v_mul_f32_e32 v73, v87, v73
	v_mul_f32_e32 v66, v74, v66
	v_mul_f32_e32 v67, v75, v67
	v_mul_f32_e32 v68, v76, v68
	v_mul_f32_e32 v69, v77, v69
	v_mul_f32_e32 v54, v62, v54
	v_mul_f32_e32 v55, v63, v55
	v_mul_f32_e32 v56, v64, v56
	v_mul_f32_e32 v57, v65, v57
	v_mul_f32_e32 v50, v58, v50
	v_mul_f32_e32 v51, v59, v51
	v_mul_f32_e32 v52, v60, v52
	v_mul_f32_e32 v53, v61, v53
	v_mul_f32_e32 v38, v46, v38
	v_mul_f32_e32 v39, v47, v39
	v_mul_f32_e32 v40, v48, v40
	v_mul_f32_e32 v41, v49, v41
	v_mul_f32_e32 v34, v42, v34
	v_mul_f32_e32 v35, v43, v35
	v_mul_f32_e32 v36, v44, v36
	v_mul_f32_e32 v37, v45, v37
	v_mul_f32_e32 v22, v30, v22
	v_mul_f32_e32 v23, v31, v23
	v_mul_f32_e32 v24, v32, v24
	v_mul_f32_e32 v25, v33, v25
	v_mul_f32_e32 v18, v26, v18
	v_mul_f32_e32 v19, v27, v19
	v_mul_f32_e32 v20, v28, v20
	v_mul_f32_e32 v21, v29, v21
	v_mul_f32_e32 v6, v14, v6
	v_mul_f32_e32 v7, v15, v7
	v_mul_f32_e32 v8, v16, v8
	v_mul_f32_e32 v9, v17, v9
	v_mul_f32_e32 v2, v10, v2
	v_mul_f32_e32 v3, v11, v3
	v_mul_f32_e32 v4, v12, v4
	v_mul_f32_e32 v5, v13, v5
	s_and_b64 vcc, exec, s[8:9]
	s_cbranch_vccz .LBB0_639
	s_barrier
